# combo23 with forward substitution's in-block 8x8 solve distributed over row lanes (DPP broadcasts), each lane reads only its own row of the diagonal block
# speedup vs baseline: 1.0072x; 1.0028x over previous
; #define LAS __attribute__((address_space(3)))
; __device__ __forceinline__ bf16_t f2bf(float f) { return (bf16_t)(cvt_pk_bf16(f, 0.f) & 0xffffu); }
; __device__ __forceinline__ void dn_prep(const Params& p, LAS unsigned char* lds) {
;     ...
;         if (wid == 0) {
;             float T[64];
;             int zoff; asm volatile("v_mov_b32 %0, 0" : "=v"(zoff));
;             const LAS float* Asz = As + zoff;
;             const float bc = beta_s[lane], wcf = bc * __expf(G_s[lane]);
;             int lo2 = lane; asm volatile("" : "+v"(lo2));
;             LAS bf16_t* tub = Tu + lo2; LAS bf16_t* twb = Tw + lo2;
;             f32x4 rlo[2][8], rhi[8];
;             T[0] = (lane == 0) ? 1.f : 0.f;
;             tub[0] = f2bf(T[0] * bc); twb[0] = f2bf(T[0] * wcf);
;             rlo[1][0] = *(const LAS f32x4*)(Asz + 68);
; #pragma unroll
;             for (int i = 1; i < 64; ++i) {
; #pragma unroll
;                 for (int j4 = 8; j4 < (i + 3) / 4; ++j4) rhi[j4 - 8] = *(const LAS f32x4*)(Asz + i * 68 + j4 * 4);
;                 if (i + 1 < 64) {
; #pragma unroll
;                     for (int j4 = 0; j4 < ((i + 4) / 4 < 8 ? (i + 4) / 4 : 8); ++j4) rlo[(i + 1) & 1][j4] = *(const LAS f32x4*)(Asz + (i + 1) * 68 + j4 * 4);
;                 }
;                 float a0 = (lane == i) ? 1.f : 0.f, a1 = 0.f, a2 = 0.f, a3 = 0.f;
; #pragma unroll
;                 for (int j4 = 0; j4 < (i + 3) / 4; ++j4) {
;                     const f32x4 av = (j4 < 8) ? rlo[i & 1][j4 & 7] : rhi[(j4 - 8) & 7];
;                     if (j4 * 4 + 0 < i) a0 -= av[0] * T[j4 * 4 + 0];
;                     if (j4 * 4 + 1 < i) a1 -= av[1] * T[j4 * 4 + 1];
;                     if (j4 * 4 + 2 < i) a2 -= av[2] * T[j4 * 4 + 2];
;                     if (j4 * 4 + 3 < i) a3 -= av[3] * T[j4 * 4 + 3];
;                 }
;                 T[i] = (a0 + a1) + (a2 + a3);
;                 tub[i * 72] = f2bf(T[i] * bc); twb[i * 72] = f2bf(T[i] * wcf);
;                 __builtin_amdgcn_sched_barrier(0);
;             }
;         }
.LBB0_375:
	s_or_b64 exec, exec, s[24:25]
	s_waitcnt lgkmcnt(0)
	s_barrier
	s_and_b64 s[0:1], s[2:3], s[68:69]
	s_xor_b64 s[0:1], s[0:1], -1
	s_and_saveexec_b64 s[6:7], s[0:1]
	s_xor_b64 s[24:25], exec, s[6:7]
	s_cbranch_execz .LBB0_379
	s_mov_b64 s[28:29], exec
	s_and_b64 vcc, exec, s[68:69]
	s_cbranch_vccnz .LBB0_378
	v_readfirstlane_b32 s1, v184
	v_and_b32_e32 v7, 63, v184
	s_nop 3
	s_lshr_b32 s1, s1, 6
	v_and_b32_e32 v6, 7, v7
	v_lshrrev_b32_e32 v7, 3, v7
	s_lshl_b32 s32, s1, 3
	s_movk_i32 s89, 0x90
	s_mov_b32 s6, 0x02020202
	s_mov_b32 s7, 0x02020202
	s_mov_b32 s68, 0x04040404
	s_mov_b32 s69, 0x04040404
	s_mov_b32 s92, 0x08080808
	s_mov_b32 s93, 0x08080808
	s_mov_b32 s94, 0x10101010
	s_mov_b32 s95, 0x10101010
	s_mov_b32 s96, 0x20202020
	s_mov_b32 s97, 0x20202020
	s_mov_b32 s98, 0x40404040
	s_mov_b32 s99, 0x40404040
	s_mov_b32 s100, 0x80808080
	s_mov_b32 s101, 0x80808080
	v_add_u32_e32 v128, s32, v7
	v_cmp_eq_u32_e32 vcc, 0, v7
	s_nop 1
	v_cndmask_b32_e64 v16, 0, 1.0, vcc
	v_cmp_eq_u32_e32 vcc, 1, v7
	s_nop 1
	v_cndmask_b32_e64 v17, 0, 1.0, vcc
	v_cmp_eq_u32_e32 vcc, 2, v7
	s_nop 1
	v_cndmask_b32_e64 v18, 0, 1.0, vcc
	v_cmp_eq_u32_e32 vcc, 3, v7
	s_nop 1
	v_cndmask_b32_e64 v19, 0, 1.0, vcc
	v_cmp_eq_u32_e32 vcc, 4, v7
	s_nop 1
	v_cndmask_b32_e64 v20, 0, 1.0, vcc
	v_cmp_eq_u32_e32 vcc, 5, v7
	s_nop 1
	v_cndmask_b32_e64 v21, 0, 1.0, vcc
	v_cmp_eq_u32_e32 vcc, 6, v7
	s_nop 1
	v_cndmask_b32_e64 v22, 0, 1.0, vcc
	v_cmp_eq_u32_e32 vcc, 7, v7
	s_nop 1
	v_cndmask_b32_e64 v23, 0, 1.0, vcc
	v_lshl_add_u32 v0, v6, 2, s13
	v_mov_b32_e32 v1, s13
	v_mov_b32_e32 v40, 0x110
	v_mad_u32_u24 v40, v6, v40, v1
	v_lshlrev_b32_e32 v2, 1, v128
	v_mad_u32_u24 v2, v6, s89, v2
	v_add_u32_e32 v3, 0x18000, v2
	v_add_u32_e32 v2, 0x15c00, v2
	v_lshlrev_b32_e32 v129, 2, v128
	v_add_u32_e32 v129, 0x1a400, v129
	ds_read_b32 v4, v129
	ds_read_b32 v5, v129 offset:256
	ds_read_b128 v[32:35], v40 offset:0
	ds_read_b128 v[36:39], v40 offset:16
	v_mov_b32_e32 v8, 0
	v_mov_b32_e32 v9, 0
	v_mov_b32_e32 v10, 0
	v_mov_b32_e32 v11, 0
	v_mov_b32_e32 v12, 0
	v_mov_b32_e32 v13, 0
	v_mov_b32_e32 v14, 0
	v_mov_b32_e32 v15, 0
	v_mov_b32_e32 v6, 0
	s_mov_b32 s91, 1.0
	s_waitcnt lgkmcnt(2)
	v_mul_f32_e32 v5, 0x3fb8aa3b, v5
	v_exp_f32_e32 v5, v5
	s_nop 0
	v_mul_f32_e32 v5, v4, v5
.Lfs_b0:
	s_cmp_gt_u32 s1, 0
	s_cbranch_scc1 .Lfs_z0
	v_mul_f32_e32 v24, s91, v16
	v_mul_f32_e32 v25, s91, v17
	v_mul_f32_e32 v26, s91, v18
	v_mul_f32_e32 v27, s91, v19
	v_mul_f32_e32 v28, s91, v20
	v_mul_f32_e32 v29, s91, v21
	v_mul_f32_e32 v30, s91, v22
	v_mul_f32_e32 v31, s91, v23
	s_waitcnt lgkmcnt(0)
	ds_read_b32 v72, v0 offset:2176
	ds_read_b32 v79, v0 offset:2448
	ds_read_b32 v86, v0 offset:2720
	ds_read_b32 v93, v0 offset:2992
	ds_read_b32 v100, v0 offset:3264
	ds_read_b32 v107, v0 offset:3536
	ds_read_b32 v114, v0 offset:3808
	ds_read_b32 v121, v0 offset:4080
	v_mov_b32_e32 v8, v24
	v_cndmask_b32_e64 v8, v8, v25, s[6:7]
	v_cndmask_b32_e64 v8, v8, v26, s[68:69]
	v_cndmask_b32_e64 v8, v8, v27, s[92:93]
	v_cndmask_b32_e64 v8, v8, v28, s[94:95]
	v_cndmask_b32_e64 v8, v8, v29, s[96:97]
	v_cndmask_b32_e64 v8, v8, v30, s[98:99]
	v_cndmask_b32_e64 v8, v8, v31, s[100:101]
	s_nop 1
	v_mov_b32_dpp v41, v8 quad_perm:[0,0,0,0] row_mask:0xf bank_mask:0xf
	s_nop 1
	v_mov_b32_dpp v41, v41 row_half_mirror row_mask:0xf bank_mask:0xa
	v_fma_f32 v8, -v32, v41, v8
	s_nop 1
	v_mov_b32_dpp v41, v8 quad_perm:[1,1,1,1] row_mask:0xf bank_mask:0xf
	s_nop 1
	v_mov_b32_dpp v41, v41 row_half_mirror row_mask:0xf bank_mask:0xa
	v_fma_f32 v8, -v33, v41, v8
	s_nop 1
	v_mov_b32_dpp v41, v8 quad_perm:[2,2,2,2] row_mask:0xf bank_mask:0xf
	s_nop 1
	v_mov_b32_dpp v41, v41 row_half_mirror row_mask:0xf bank_mask:0xa
	v_fma_f32 v8, -v34, v41, v8
	s_nop 1
	v_mov_b32_dpp v41, v8 quad_perm:[3,3,3,3] row_mask:0xf bank_mask:0xf
	s_nop 1
	v_mov_b32_dpp v41, v41 row_half_mirror row_mask:0xf bank_mask:0xa
	v_fma_f32 v8, -v35, v41, v8
	s_nop 1
	v_mov_b32_dpp v41, v8 quad_perm:[0,0,0,0] row_mask:0xf bank_mask:0xf
	v_fma_f32 v8, -v36, v41, v8
	s_nop 1
	v_mov_b32_dpp v41, v8 quad_perm:[1,1,1,1] row_mask:0xf bank_mask:0xf
	v_fma_f32 v8, -v37, v41, v8
	s_nop 1
	v_mov_b32_dpp v41, v8 quad_perm:[2,2,2,2] row_mask:0xf bank_mask:0xf
	v_fma_f32 v8, -v38, v41, v8
	ds_read_b128 v[32:35], v40 offset:2208
	ds_read_b128 v[36:39], v40 offset:2224
	v_mul_f32_e32 v128, v4, v8
	v_mul_f32_e32 v129, v5, v8
	v_cvt_pk_bf16_f32 v128, v128, v128
	v_cvt_pk_bf16_f32 v129, v129, v129
	ds_write_b16 v2, v128 offset:0
	ds_write_b16 v3, v129 offset:0
	s_mov_b32 s91, 0
; #define LAS __attribute__((address_space(3)))
; __device__ __forceinline__ bf16_t f2bf(float f) { return (bf16_t)(cvt_pk_bf16(f, 0.f) & 0xffffu); }
; __device__ __forceinline__ void dn_prep(const Params& p, LAS unsigned char* lds) {
;     ...
;             for (int i = 1; i < 64; ++i) {
; #pragma unroll
;                 for (int j4 = 8; j4 < (i + 3) / 4; ++j4) rhi[j4 - 8] = *(const LAS f32x4*)(Asz + i * 68 + j4 * 4);
;                 if (i + 1 < 64) {
; #pragma unroll
;                     for (int j4 = 0; j4 < ((i + 4) / 4 < 8 ? (i + 4) / 4 : 8); ++j4) rlo[(i + 1) & 1][j4] = *(const LAS f32x4*)(Asz + (i + 1) * 68 + j4 * 4);
;                 }
;                 float a0 = (lane == i) ? 1.f : 0.f, a1 = 0.f, a2 = 0.f, a3 = 0.f;
; #pragma unroll
;                 for (int j4 = 0; j4 < (i + 3) / 4; ++j4) {
;                     const f32x4 av = (j4 < 8) ? rlo[i & 1][j4 & 7] : rhi[(j4 - 8) & 7];
;                     if (j4 * 4 + 0 < i) a0 -= av[0] * T[j4 * 4 + 0];
;                     if (j4 * 4 + 1 < i) a1 -= av[1] * T[j4 * 4 + 1];
;                     if (j4 * 4 + 2 < i) a2 -= av[2] * T[j4 * 4 + 2];
;                     if (j4 * 4 + 3 < i) a3 -= av[3] * T[j4 * 4 + 3];
;                 }
;                 T[i] = (a0 + a1) + (a2 + a3);
;                 tub[i * 72] = f2bf(T[i] * bc); twb[i * 72] = f2bf(T[i] * wcf);
.Lfs_b1:
	s_cmp_gt_u32 s1, 1
	s_cbranch_scc1 .Lfs_z1
	s_waitcnt lgkmcnt(4)
	v_mul_f32_e32 v24, v72, v8
	v_mul_f32_e32 v25, v79, v8
	v_mul_f32_e32 v26, v86, v8
	v_mul_f32_e32 v27, v93, v8
	v_mul_f32_e32 v28, v100, v8
	v_mul_f32_e32 v29, v107, v8
	v_mul_f32_e32 v30, v114, v8
	v_mul_f32_e32 v31, v121, v8
	v_add_f32_dpp v24, v24, v24 quad_perm:[1,0,3,2] row_mask:0xf bank_mask:0xf bound_ctrl:1
	v_add_f32_dpp v25, v25, v25 quad_perm:[1,0,3,2] row_mask:0xf bank_mask:0xf bound_ctrl:1
	v_add_f32_dpp v26, v26, v26 quad_perm:[1,0,3,2] row_mask:0xf bank_mask:0xf bound_ctrl:1
	v_add_f32_dpp v27, v27, v27 quad_perm:[1,0,3,2] row_mask:0xf bank_mask:0xf bound_ctrl:1
	v_add_f32_dpp v28, v28, v28 quad_perm:[1,0,3,2] row_mask:0xf bank_mask:0xf bound_ctrl:1
	v_add_f32_dpp v29, v29, v29 quad_perm:[1,0,3,2] row_mask:0xf bank_mask:0xf bound_ctrl:1
	v_add_f32_dpp v30, v30, v30 quad_perm:[1,0,3,2] row_mask:0xf bank_mask:0xf bound_ctrl:1
	v_add_f32_dpp v31, v31, v31 quad_perm:[1,0,3,2] row_mask:0xf bank_mask:0xf bound_ctrl:1
	v_add_f32_dpp v24, v24, v24 quad_perm:[2,3,0,1] row_mask:0xf bank_mask:0xf bound_ctrl:1
	v_add_f32_dpp v25, v25, v25 quad_perm:[2,3,0,1] row_mask:0xf bank_mask:0xf bound_ctrl:1
	v_add_f32_dpp v26, v26, v26 quad_perm:[2,3,0,1] row_mask:0xf bank_mask:0xf bound_ctrl:1
	v_add_f32_dpp v27, v27, v27 quad_perm:[2,3,0,1] row_mask:0xf bank_mask:0xf bound_ctrl:1
	v_add_f32_dpp v28, v28, v28 quad_perm:[2,3,0,1] row_mask:0xf bank_mask:0xf bound_ctrl:1
	v_add_f32_dpp v29, v29, v29 quad_perm:[2,3,0,1] row_mask:0xf bank_mask:0xf bound_ctrl:1
	v_add_f32_dpp v30, v30, v30 quad_perm:[2,3,0,1] row_mask:0xf bank_mask:0xf bound_ctrl:1
	v_add_f32_dpp v31, v31, v31 quad_perm:[2,3,0,1] row_mask:0xf bank_mask:0xf bound_ctrl:1
	v_add_f32_dpp v24, v24, v24 row_half_mirror row_mask:0xf bank_mask:0xf bound_ctrl:1
	v_add_f32_dpp v25, v25, v25 row_half_mirror row_mask:0xf bank_mask:0xf bound_ctrl:1
	v_add_f32_dpp v26, v26, v26 row_half_mirror row_mask:0xf bank_mask:0xf bound_ctrl:1
	v_add_f32_dpp v27, v27, v27 row_half_mirror row_mask:0xf bank_mask:0xf bound_ctrl:1
	v_add_f32_dpp v28, v28, v28 row_half_mirror row_mask:0xf bank_mask:0xf bound_ctrl:1
	v_add_f32_dpp v29, v29, v29 row_half_mirror row_mask:0xf bank_mask:0xf bound_ctrl:1
	v_add_f32_dpp v30, v30, v30 row_half_mirror row_mask:0xf bank_mask:0xf bound_ctrl:1
	v_add_f32_dpp v31, v31, v31 row_half_mirror row_mask:0xf bank_mask:0xf bound_ctrl:1
	v_fma_f32 v24, v16, s91, -v24
	v_fma_f32 v25, v17, s91, -v25
	v_fma_f32 v26, v18, s91, -v26
	v_fma_f32 v27, v19, s91, -v27
	v_fma_f32 v28, v20, s91, -v28
	v_fma_f32 v29, v21, s91, -v29
	v_fma_f32 v30, v22, s91, -v30
	v_fma_f32 v31, v23, s91, -v31
	s_waitcnt lgkmcnt(0)
	ds_read_b32 v72, v0 offset:4352
	ds_read_b32 v73, v0 offset:4384
	ds_read_b32 v79, v0 offset:4624
	ds_read_b32 v80, v0 offset:4656
	ds_read_b32 v86, v0 offset:4896
	ds_read_b32 v87, v0 offset:4928
	ds_read_b32 v93, v0 offset:5168
	ds_read_b32 v94, v0 offset:5200
	ds_read_b32 v100, v0 offset:5440
	ds_read_b32 v101, v0 offset:5472
	ds_read_b32 v107, v0 offset:5712
	ds_read_b32 v108, v0 offset:5744
	ds_read_b32 v114, v0 offset:5984
	ds_read_b32 v115, v0 offset:6016
	ds_read_b32 v121, v0 offset:6256
	ds_read_b32 v122, v0 offset:6288
	v_mov_b32_e32 v9, v24
	v_cndmask_b32_e64 v9, v9, v25, s[6:7]
	v_cndmask_b32_e64 v9, v9, v26, s[68:69]
	v_cndmask_b32_e64 v9, v9, v27, s[92:93]
	v_cndmask_b32_e64 v9, v9, v28, s[94:95]
	v_cndmask_b32_e64 v9, v9, v29, s[96:97]
	v_cndmask_b32_e64 v9, v9, v30, s[98:99]
	v_cndmask_b32_e64 v9, v9, v31, s[100:101]
	s_nop 1
	v_mov_b32_dpp v41, v9 quad_perm:[0,0,0,0] row_mask:0xf bank_mask:0xf
	s_nop 1
	v_mov_b32_dpp v41, v41 row_half_mirror row_mask:0xf bank_mask:0xa
	v_fma_f32 v9, -v32, v41, v9
	s_nop 1
	v_mov_b32_dpp v41, v9 quad_perm:[1,1,1,1] row_mask:0xf bank_mask:0xf
	s_nop 1
	v_mov_b32_dpp v41, v41 row_half_mirror row_mask:0xf bank_mask:0xa
	v_fma_f32 v9, -v33, v41, v9
	s_nop 1
	v_mov_b32_dpp v41, v9 quad_perm:[2,2,2,2] row_mask:0xf bank_mask:0xf
	s_nop 1
	v_mov_b32_dpp v41, v41 row_half_mirror row_mask:0xf bank_mask:0xa
	v_fma_f32 v9, -v34, v41, v9
	s_nop 1
	v_mov_b32_dpp v41, v9 quad_perm:[3,3,3,3] row_mask:0xf bank_mask:0xf
	s_nop 1
	v_mov_b32_dpp v41, v41 row_half_mirror row_mask:0xf bank_mask:0xa
	v_fma_f32 v9, -v35, v41, v9
	s_nop 1
	v_mov_b32_dpp v41, v9 quad_perm:[0,0,0,0] row_mask:0xf bank_mask:0xf
	v_fma_f32 v9, -v36, v41, v9
	s_nop 1
	v_mov_b32_dpp v41, v9 quad_perm:[1,1,1,1] row_mask:0xf bank_mask:0xf
	v_fma_f32 v9, -v37, v41, v9
	s_nop 1
	v_mov_b32_dpp v41, v9 quad_perm:[2,2,2,2] row_mask:0xf bank_mask:0xf
	v_fma_f32 v9, -v38, v41, v9
	ds_read_b128 v[32:35], v40 offset:4416
	ds_read_b128 v[36:39], v40 offset:4432
	v_mul_f32_e32 v128, v4, v9
	v_mul_f32_e32 v129, v5, v9
	v_cvt_pk_bf16_f32 v128, v128, v128
	v_cvt_pk_bf16_f32 v129, v129, v129
	ds_write_b16 v2, v128 offset:1152
	ds_write_b16 v3, v129 offset:1152
	s_mov_b32 s91, 0
; #define LAS __attribute__((address_space(3)))
; __device__ __forceinline__ bf16_t f2bf(float f) { return (bf16_t)(cvt_pk_bf16(f, 0.f) & 0xffffu); }
; __device__ __forceinline__ void dn_prep(const Params& p, LAS unsigned char* lds) {
;     ...
;             for (int i = 1; i < 64; ++i) {
; #pragma unroll
;                 for (int j4 = 8; j4 < (i + 3) / 4; ++j4) rhi[j4 - 8] = *(const LAS f32x4*)(Asz + i * 68 + j4 * 4);
;                 if (i + 1 < 64) {
; #pragma unroll
;                     for (int j4 = 0; j4 < ((i + 4) / 4 < 8 ? (i + 4) / 4 : 8); ++j4) rlo[(i + 1) & 1][j4] = *(const LAS f32x4*)(Asz + (i + 1) * 68 + j4 * 4);
;                 }
;                 float a0 = (lane == i) ? 1.f : 0.f, a1 = 0.f, a2 = 0.f, a3 = 0.f;
; #pragma unroll
;                 for (int j4 = 0; j4 < (i + 3) / 4; ++j4) {
;                     const f32x4 av = (j4 < 8) ? rlo[i & 1][j4 & 7] : rhi[(j4 - 8) & 7];
;                     if (j4 * 4 + 0 < i) a0 -= av[0] * T[j4 * 4 + 0];
;                     if (j4 * 4 + 1 < i) a1 -= av[1] * T[j4 * 4 + 1];
;                     if (j4 * 4 + 2 < i) a2 -= av[2] * T[j4 * 4 + 2];
;                     if (j4 * 4 + 3 < i) a3 -= av[3] * T[j4 * 4 + 3];
;                 }
;                 T[i] = (a0 + a1) + (a2 + a3);
;                 tub[i * 72] = f2bf(T[i] * bc); twb[i * 72] = f2bf(T[i] * wcf);
.Lfs_b2:
	s_cmp_gt_u32 s1, 2
	s_cbranch_scc1 .Lfs_z2
	s_waitcnt lgkmcnt(4)
	v_mul_f32_e32 v24, v72, v8
	v_mul_f32_e32 v25, v79, v8
	v_mul_f32_e32 v26, v86, v8
	v_mul_f32_e32 v27, v93, v8
	v_mul_f32_e32 v28, v100, v8
	v_mul_f32_e32 v29, v107, v8
	v_mul_f32_e32 v30, v114, v8
	v_mul_f32_e32 v31, v121, v8
	v_fmac_f32_e32 v24, v73, v9
	v_fmac_f32_e32 v25, v80, v9
	v_fmac_f32_e32 v26, v87, v9
	v_fmac_f32_e32 v27, v94, v9
	v_fmac_f32_e32 v28, v101, v9
	v_fmac_f32_e32 v29, v108, v9
	v_fmac_f32_e32 v30, v115, v9
	v_fmac_f32_e32 v31, v122, v9
	v_add_f32_dpp v24, v24, v24 quad_perm:[1,0,3,2] row_mask:0xf bank_mask:0xf bound_ctrl:1
	v_add_f32_dpp v25, v25, v25 quad_perm:[1,0,3,2] row_mask:0xf bank_mask:0xf bound_ctrl:1
	v_add_f32_dpp v26, v26, v26 quad_perm:[1,0,3,2] row_mask:0xf bank_mask:0xf bound_ctrl:1
	v_add_f32_dpp v27, v27, v27 quad_perm:[1,0,3,2] row_mask:0xf bank_mask:0xf bound_ctrl:1
	v_add_f32_dpp v28, v28, v28 quad_perm:[1,0,3,2] row_mask:0xf bank_mask:0xf bound_ctrl:1
	v_add_f32_dpp v29, v29, v29 quad_perm:[1,0,3,2] row_mask:0xf bank_mask:0xf bound_ctrl:1
	v_add_f32_dpp v30, v30, v30 quad_perm:[1,0,3,2] row_mask:0xf bank_mask:0xf bound_ctrl:1
	v_add_f32_dpp v31, v31, v31 quad_perm:[1,0,3,2] row_mask:0xf bank_mask:0xf bound_ctrl:1
	v_add_f32_dpp v24, v24, v24 quad_perm:[2,3,0,1] row_mask:0xf bank_mask:0xf bound_ctrl:1
	v_add_f32_dpp v25, v25, v25 quad_perm:[2,3,0,1] row_mask:0xf bank_mask:0xf bound_ctrl:1
	v_add_f32_dpp v26, v26, v26 quad_perm:[2,3,0,1] row_mask:0xf bank_mask:0xf bound_ctrl:1
	v_add_f32_dpp v27, v27, v27 quad_perm:[2,3,0,1] row_mask:0xf bank_mask:0xf bound_ctrl:1
	v_add_f32_dpp v28, v28, v28 quad_perm:[2,3,0,1] row_mask:0xf bank_mask:0xf bound_ctrl:1
	v_add_f32_dpp v29, v29, v29 quad_perm:[2,3,0,1] row_mask:0xf bank_mask:0xf bound_ctrl:1
	v_add_f32_dpp v30, v30, v30 quad_perm:[2,3,0,1] row_mask:0xf bank_mask:0xf bound_ctrl:1
	v_add_f32_dpp v31, v31, v31 quad_perm:[2,3,0,1] row_mask:0xf bank_mask:0xf bound_ctrl:1
	v_add_f32_dpp v24, v24, v24 row_half_mirror row_mask:0xf bank_mask:0xf bound_ctrl:1
	v_add_f32_dpp v25, v25, v25 row_half_mirror row_mask:0xf bank_mask:0xf bound_ctrl:1
	v_add_f32_dpp v26, v26, v26 row_half_mirror row_mask:0xf bank_mask:0xf bound_ctrl:1
	v_add_f32_dpp v27, v27, v27 row_half_mirror row_mask:0xf bank_mask:0xf bound_ctrl:1
	v_add_f32_dpp v28, v28, v28 row_half_mirror row_mask:0xf bank_mask:0xf bound_ctrl:1
	v_add_f32_dpp v29, v29, v29 row_half_mirror row_mask:0xf bank_mask:0xf bound_ctrl:1
	v_add_f32_dpp v30, v30, v30 row_half_mirror row_mask:0xf bank_mask:0xf bound_ctrl:1
	v_add_f32_dpp v31, v31, v31 row_half_mirror row_mask:0xf bank_mask:0xf bound_ctrl:1
	v_fma_f32 v24, v16, s91, -v24
	v_fma_f32 v25, v17, s91, -v25
	v_fma_f32 v26, v18, s91, -v26
	v_fma_f32 v27, v19, s91, -v27
	v_fma_f32 v28, v20, s91, -v28
	v_fma_f32 v29, v21, s91, -v29
	v_fma_f32 v30, v22, s91, -v30
	v_fma_f32 v31, v23, s91, -v31
	s_waitcnt lgkmcnt(0)
	ds_read_b32 v72, v0 offset:6528
	ds_read_b32 v73, v0 offset:6560
	ds_read_b32 v74, v0 offset:6592
	ds_read_b32 v79, v0 offset:6800
	ds_read_b32 v80, v0 offset:6832
	ds_read_b32 v81, v0 offset:6864
	ds_read_b32 v86, v0 offset:7072
	ds_read_b32 v87, v0 offset:7104
	ds_read_b32 v88, v0 offset:7136
	ds_read_b32 v93, v0 offset:7344
	ds_read_b32 v94, v0 offset:7376
	ds_read_b32 v95, v0 offset:7408
	ds_read_b32 v100, v0 offset:7616
	ds_read_b32 v101, v0 offset:7648
	ds_read_b32 v102, v0 offset:7680
	ds_read_b32 v107, v0 offset:7888
	ds_read_b32 v108, v0 offset:7920
	ds_read_b32 v109, v0 offset:7952
	ds_read_b32 v114, v0 offset:8160
	ds_read_b32 v115, v0 offset:8192
	ds_read_b32 v116, v0 offset:8224
	ds_read_b32 v121, v0 offset:8432
	ds_read_b32 v122, v0 offset:8464
	ds_read_b32 v123, v0 offset:8496
	v_mov_b32_e32 v10, v24
	v_cndmask_b32_e64 v10, v10, v25, s[6:7]
	v_cndmask_b32_e64 v10, v10, v26, s[68:69]
	v_cndmask_b32_e64 v10, v10, v27, s[92:93]
	v_cndmask_b32_e64 v10, v10, v28, s[94:95]
	v_cndmask_b32_e64 v10, v10, v29, s[96:97]
	v_cndmask_b32_e64 v10, v10, v30, s[98:99]
	v_cndmask_b32_e64 v10, v10, v31, s[100:101]
	s_nop 1
	v_mov_b32_dpp v41, v10 quad_perm:[0,0,0,0] row_mask:0xf bank_mask:0xf
	s_nop 1
	v_mov_b32_dpp v41, v41 row_half_mirror row_mask:0xf bank_mask:0xa
	v_fma_f32 v10, -v32, v41, v10
	s_nop 1
	v_mov_b32_dpp v41, v10 quad_perm:[1,1,1,1] row_mask:0xf bank_mask:0xf
	s_nop 1
	v_mov_b32_dpp v41, v41 row_half_mirror row_mask:0xf bank_mask:0xa
	v_fma_f32 v10, -v33, v41, v10
	s_nop 1
	v_mov_b32_dpp v41, v10 quad_perm:[2,2,2,2] row_mask:0xf bank_mask:0xf
	s_nop 1
	v_mov_b32_dpp v41, v41 row_half_mirror row_mask:0xf bank_mask:0xa
	v_fma_f32 v10, -v34, v41, v10
	s_nop 1
	v_mov_b32_dpp v41, v10 quad_perm:[3,3,3,3] row_mask:0xf bank_mask:0xf
	s_nop 1
	v_mov_b32_dpp v41, v41 row_half_mirror row_mask:0xf bank_mask:0xa
	v_fma_f32 v10, -v35, v41, v10
	s_nop 1
	v_mov_b32_dpp v41, v10 quad_perm:[0,0,0,0] row_mask:0xf bank_mask:0xf
	v_fma_f32 v10, -v36, v41, v10
	s_nop 1
	v_mov_b32_dpp v41, v10 quad_perm:[1,1,1,1] row_mask:0xf bank_mask:0xf
	v_fma_f32 v10, -v37, v41, v10
	s_nop 1
	v_mov_b32_dpp v41, v10 quad_perm:[2,2,2,2] row_mask:0xf bank_mask:0xf
	v_fma_f32 v10, -v38, v41, v10
	ds_read_b128 v[32:35], v40 offset:6624
	ds_read_b128 v[36:39], v40 offset:6640
	v_mul_f32_e32 v128, v4, v10
	v_mul_f32_e32 v129, v5, v10
	v_cvt_pk_bf16_f32 v128, v128, v128
	v_cvt_pk_bf16_f32 v129, v129, v129
	ds_write_b16 v2, v128 offset:2304
	ds_write_b16 v3, v129 offset:2304
	s_mov_b32 s91, 0
; #define LAS __attribute__((address_space(3)))
; __device__ __forceinline__ bf16_t f2bf(float f) { return (bf16_t)(cvt_pk_bf16(f, 0.f) & 0xffffu); }
; __device__ __forceinline__ void dn_prep(const Params& p, LAS unsigned char* lds) {
;     ...
;             for (int i = 1; i < 64; ++i) {
; #pragma unroll
;                 for (int j4 = 8; j4 < (i + 3) / 4; ++j4) rhi[j4 - 8] = *(const LAS f32x4*)(Asz + i * 68 + j4 * 4);
;                 if (i + 1 < 64) {
; #pragma unroll
;                     for (int j4 = 0; j4 < ((i + 4) / 4 < 8 ? (i + 4) / 4 : 8); ++j4) rlo[(i + 1) & 1][j4] = *(const LAS f32x4*)(Asz + (i + 1) * 68 + j4 * 4);
;                 }
;                 float a0 = (lane == i) ? 1.f : 0.f, a1 = 0.f, a2 = 0.f, a3 = 0.f;
; #pragma unroll
;                 for (int j4 = 0; j4 < (i + 3) / 4; ++j4) {
;                     const f32x4 av = (j4 < 8) ? rlo[i & 1][j4 & 7] : rhi[(j4 - 8) & 7];
;                     if (j4 * 4 + 0 < i) a0 -= av[0] * T[j4 * 4 + 0];
;                     if (j4 * 4 + 1 < i) a1 -= av[1] * T[j4 * 4 + 1];
;                     if (j4 * 4 + 2 < i) a2 -= av[2] * T[j4 * 4 + 2];
;                     if (j4 * 4 + 3 < i) a3 -= av[3] * T[j4 * 4 + 3];
;                 }
;                 T[i] = (a0 + a1) + (a2 + a3);
;                 tub[i * 72] = f2bf(T[i] * bc); twb[i * 72] = f2bf(T[i] * wcf);
.Lfs_b3:
	s_cmp_gt_u32 s1, 3
	s_cbranch_scc1 .Lfs_z3
	s_waitcnt lgkmcnt(4)
	v_mul_f32_e32 v24, v72, v8
	v_mul_f32_e32 v25, v79, v8
	v_mul_f32_e32 v26, v86, v8
	v_mul_f32_e32 v27, v93, v8
	v_mul_f32_e32 v28, v100, v8
	v_mul_f32_e32 v29, v107, v8
	v_mul_f32_e32 v30, v114, v8
	v_mul_f32_e32 v31, v121, v8
	v_fmac_f32_e32 v24, v73, v9
	v_fmac_f32_e32 v25, v80, v9
	v_fmac_f32_e32 v26, v87, v9
	v_fmac_f32_e32 v27, v94, v9
	v_fmac_f32_e32 v28, v101, v9
	v_fmac_f32_e32 v29, v108, v9
	v_fmac_f32_e32 v30, v115, v9
	v_fmac_f32_e32 v31, v122, v9
	v_fmac_f32_e32 v24, v74, v10
	v_fmac_f32_e32 v25, v81, v10
	v_fmac_f32_e32 v26, v88, v10
	v_fmac_f32_e32 v27, v95, v10
	v_fmac_f32_e32 v28, v102, v10
	v_fmac_f32_e32 v29, v109, v10
	v_fmac_f32_e32 v30, v116, v10
	v_fmac_f32_e32 v31, v123, v10
	v_add_f32_dpp v24, v24, v24 quad_perm:[1,0,3,2] row_mask:0xf bank_mask:0xf bound_ctrl:1
	v_add_f32_dpp v25, v25, v25 quad_perm:[1,0,3,2] row_mask:0xf bank_mask:0xf bound_ctrl:1
	v_add_f32_dpp v26, v26, v26 quad_perm:[1,0,3,2] row_mask:0xf bank_mask:0xf bound_ctrl:1
	v_add_f32_dpp v27, v27, v27 quad_perm:[1,0,3,2] row_mask:0xf bank_mask:0xf bound_ctrl:1
	v_add_f32_dpp v28, v28, v28 quad_perm:[1,0,3,2] row_mask:0xf bank_mask:0xf bound_ctrl:1
	v_add_f32_dpp v29, v29, v29 quad_perm:[1,0,3,2] row_mask:0xf bank_mask:0xf bound_ctrl:1
	v_add_f32_dpp v30, v30, v30 quad_perm:[1,0,3,2] row_mask:0xf bank_mask:0xf bound_ctrl:1
	v_add_f32_dpp v31, v31, v31 quad_perm:[1,0,3,2] row_mask:0xf bank_mask:0xf bound_ctrl:1
	v_add_f32_dpp v24, v24, v24 quad_perm:[2,3,0,1] row_mask:0xf bank_mask:0xf bound_ctrl:1
	v_add_f32_dpp v25, v25, v25 quad_perm:[2,3,0,1] row_mask:0xf bank_mask:0xf bound_ctrl:1
	v_add_f32_dpp v26, v26, v26 quad_perm:[2,3,0,1] row_mask:0xf bank_mask:0xf bound_ctrl:1
	v_add_f32_dpp v27, v27, v27 quad_perm:[2,3,0,1] row_mask:0xf bank_mask:0xf bound_ctrl:1
	v_add_f32_dpp v28, v28, v28 quad_perm:[2,3,0,1] row_mask:0xf bank_mask:0xf bound_ctrl:1
	v_add_f32_dpp v29, v29, v29 quad_perm:[2,3,0,1] row_mask:0xf bank_mask:0xf bound_ctrl:1
	v_add_f32_dpp v30, v30, v30 quad_perm:[2,3,0,1] row_mask:0xf bank_mask:0xf bound_ctrl:1
	v_add_f32_dpp v31, v31, v31 quad_perm:[2,3,0,1] row_mask:0xf bank_mask:0xf bound_ctrl:1
	v_add_f32_dpp v24, v24, v24 row_half_mirror row_mask:0xf bank_mask:0xf bound_ctrl:1
	v_add_f32_dpp v25, v25, v25 row_half_mirror row_mask:0xf bank_mask:0xf bound_ctrl:1
	v_add_f32_dpp v26, v26, v26 row_half_mirror row_mask:0xf bank_mask:0xf bound_ctrl:1
	v_add_f32_dpp v27, v27, v27 row_half_mirror row_mask:0xf bank_mask:0xf bound_ctrl:1
	v_add_f32_dpp v28, v28, v28 row_half_mirror row_mask:0xf bank_mask:0xf bound_ctrl:1
	v_add_f32_dpp v29, v29, v29 row_half_mirror row_mask:0xf bank_mask:0xf bound_ctrl:1
	v_add_f32_dpp v30, v30, v30 row_half_mirror row_mask:0xf bank_mask:0xf bound_ctrl:1
	v_add_f32_dpp v31, v31, v31 row_half_mirror row_mask:0xf bank_mask:0xf bound_ctrl:1
	v_fma_f32 v24, v16, s91, -v24
	v_fma_f32 v25, v17, s91, -v25
	v_fma_f32 v26, v18, s91, -v26
	v_fma_f32 v27, v19, s91, -v27
	v_fma_f32 v28, v20, s91, -v28
	v_fma_f32 v29, v21, s91, -v29
	v_fma_f32 v30, v22, s91, -v30
	v_fma_f32 v31, v23, s91, -v31
	s_waitcnt lgkmcnt(0)
	ds_read_b32 v72, v0 offset:8704
	ds_read_b32 v73, v0 offset:8736
	ds_read_b32 v74, v0 offset:8768
	ds_read_b32 v75, v0 offset:8800
	ds_read_b32 v79, v0 offset:8976
	ds_read_b32 v80, v0 offset:9008
	ds_read_b32 v81, v0 offset:9040
	ds_read_b32 v82, v0 offset:9072
	ds_read_b32 v86, v0 offset:9248
	ds_read_b32 v87, v0 offset:9280
	ds_read_b32 v88, v0 offset:9312
	ds_read_b32 v89, v0 offset:9344
	ds_read_b32 v93, v0 offset:9520
	ds_read_b32 v94, v0 offset:9552
	ds_read_b32 v95, v0 offset:9584
	ds_read_b32 v96, v0 offset:9616
	ds_read_b32 v100, v0 offset:9792
	ds_read_b32 v101, v0 offset:9824
	ds_read_b32 v102, v0 offset:9856
	ds_read_b32 v103, v0 offset:9888
	ds_read_b32 v107, v0 offset:10064
	ds_read_b32 v108, v0 offset:10096
	ds_read_b32 v109, v0 offset:10128
	ds_read_b32 v110, v0 offset:10160
	ds_read_b32 v114, v0 offset:10336
	ds_read_b32 v115, v0 offset:10368
	ds_read_b32 v116, v0 offset:10400
	ds_read_b32 v117, v0 offset:10432
	ds_read_b32 v121, v0 offset:10608
	ds_read_b32 v122, v0 offset:10640
	ds_read_b32 v123, v0 offset:10672
	ds_read_b32 v124, v0 offset:10704
	v_mov_b32_e32 v11, v24
	v_cndmask_b32_e64 v11, v11, v25, s[6:7]
	v_cndmask_b32_e64 v11, v11, v26, s[68:69]
	v_cndmask_b32_e64 v11, v11, v27, s[92:93]
	v_cndmask_b32_e64 v11, v11, v28, s[94:95]
	v_cndmask_b32_e64 v11, v11, v29, s[96:97]
	v_cndmask_b32_e64 v11, v11, v30, s[98:99]
	v_cndmask_b32_e64 v11, v11, v31, s[100:101]
	s_nop 1
	v_mov_b32_dpp v41, v11 quad_perm:[0,0,0,0] row_mask:0xf bank_mask:0xf
	s_nop 1
	v_mov_b32_dpp v41, v41 row_half_mirror row_mask:0xf bank_mask:0xa
	v_fma_f32 v11, -v32, v41, v11
	s_nop 1
	v_mov_b32_dpp v41, v11 quad_perm:[1,1,1,1] row_mask:0xf bank_mask:0xf
	s_nop 1
	v_mov_b32_dpp v41, v41 row_half_mirror row_mask:0xf bank_mask:0xa
	v_fma_f32 v11, -v33, v41, v11
	s_nop 1
	v_mov_b32_dpp v41, v11 quad_perm:[2,2,2,2] row_mask:0xf bank_mask:0xf
	s_nop 1
	v_mov_b32_dpp v41, v41 row_half_mirror row_mask:0xf bank_mask:0xa
	v_fma_f32 v11, -v34, v41, v11
	s_nop 1
	v_mov_b32_dpp v41, v11 quad_perm:[3,3,3,3] row_mask:0xf bank_mask:0xf
	s_nop 1
	v_mov_b32_dpp v41, v41 row_half_mirror row_mask:0xf bank_mask:0xa
	v_fma_f32 v11, -v35, v41, v11
	s_nop 1
	v_mov_b32_dpp v41, v11 quad_perm:[0,0,0,0] row_mask:0xf bank_mask:0xf
	v_fma_f32 v11, -v36, v41, v11
	s_nop 1
	v_mov_b32_dpp v41, v11 quad_perm:[1,1,1,1] row_mask:0xf bank_mask:0xf
	v_fma_f32 v11, -v37, v41, v11
	s_nop 1
	v_mov_b32_dpp v41, v11 quad_perm:[2,2,2,2] row_mask:0xf bank_mask:0xf
	v_fma_f32 v11, -v38, v41, v11
	ds_read_b128 v[32:35], v40 offset:8832
	ds_read_b128 v[36:39], v40 offset:8848
	v_mul_f32_e32 v128, v4, v11
	v_mul_f32_e32 v129, v5, v11
	v_cvt_pk_bf16_f32 v128, v128, v128
	v_cvt_pk_bf16_f32 v129, v129, v129
	ds_write_b16 v2, v128 offset:3456
	ds_write_b16 v3, v129 offset:3456
	s_mov_b32 s91, 0
; #define LAS __attribute__((address_space(3)))
; __device__ __forceinline__ bf16_t f2bf(float f) { return (bf16_t)(cvt_pk_bf16(f, 0.f) & 0xffffu); }
; __device__ __forceinline__ void dn_prep(const Params& p, LAS unsigned char* lds) {
;     ...
;             for (int i = 1; i < 64; ++i) {
; #pragma unroll
;                 for (int j4 = 8; j4 < (i + 3) / 4; ++j4) rhi[j4 - 8] = *(const LAS f32x4*)(Asz + i * 68 + j4 * 4);
;                 if (i + 1 < 64) {
; #pragma unroll
;                     for (int j4 = 0; j4 < ((i + 4) / 4 < 8 ? (i + 4) / 4 : 8); ++j4) rlo[(i + 1) & 1][j4] = *(const LAS f32x4*)(Asz + (i + 1) * 68 + j4 * 4);
;                 }
;                 float a0 = (lane == i) ? 1.f : 0.f, a1 = 0.f, a2 = 0.f, a3 = 0.f;
; #pragma unroll
;                 for (int j4 = 0; j4 < (i + 3) / 4; ++j4) {
;                     const f32x4 av = (j4 < 8) ? rlo[i & 1][j4 & 7] : rhi[(j4 - 8) & 7];
;                     if (j4 * 4 + 0 < i) a0 -= av[0] * T[j4 * 4 + 0];
;                     if (j4 * 4 + 1 < i) a1 -= av[1] * T[j4 * 4 + 1];
;                     if (j4 * 4 + 2 < i) a2 -= av[2] * T[j4 * 4 + 2];
;                     if (j4 * 4 + 3 < i) a3 -= av[3] * T[j4 * 4 + 3];
;                 }
;                 T[i] = (a0 + a1) + (a2 + a3);
;                 tub[i * 72] = f2bf(T[i] * bc); twb[i * 72] = f2bf(T[i] * wcf);
.Lfs_b4:
	s_cmp_gt_u32 s1, 4
	s_cbranch_scc1 .Lfs_z4
	s_waitcnt lgkmcnt(4)
	v_mul_f32_e32 v24, v72, v8
	v_mul_f32_e32 v25, v79, v8
	v_mul_f32_e32 v26, v86, v8
	v_mul_f32_e32 v27, v93, v8
	v_mul_f32_e32 v28, v100, v8
	v_mul_f32_e32 v29, v107, v8
	v_mul_f32_e32 v30, v114, v8
	v_mul_f32_e32 v31, v121, v8
	v_fmac_f32_e32 v24, v73, v9
	v_fmac_f32_e32 v25, v80, v9
	v_fmac_f32_e32 v26, v87, v9
	v_fmac_f32_e32 v27, v94, v9
	v_fmac_f32_e32 v28, v101, v9
	v_fmac_f32_e32 v29, v108, v9
	v_fmac_f32_e32 v30, v115, v9
	v_fmac_f32_e32 v31, v122, v9
	v_fmac_f32_e32 v24, v74, v10
	v_fmac_f32_e32 v25, v81, v10
	v_fmac_f32_e32 v26, v88, v10
	v_fmac_f32_e32 v27, v95, v10
	v_fmac_f32_e32 v28, v102, v10
	v_fmac_f32_e32 v29, v109, v10
	v_fmac_f32_e32 v30, v116, v10
	v_fmac_f32_e32 v31, v123, v10
	v_fmac_f32_e32 v24, v75, v11
	v_fmac_f32_e32 v25, v82, v11
	v_fmac_f32_e32 v26, v89, v11
	v_fmac_f32_e32 v27, v96, v11
	v_fmac_f32_e32 v28, v103, v11
	v_fmac_f32_e32 v29, v110, v11
	v_fmac_f32_e32 v30, v117, v11
	v_fmac_f32_e32 v31, v124, v11
	v_add_f32_dpp v24, v24, v24 quad_perm:[1,0,3,2] row_mask:0xf bank_mask:0xf bound_ctrl:1
	v_add_f32_dpp v25, v25, v25 quad_perm:[1,0,3,2] row_mask:0xf bank_mask:0xf bound_ctrl:1
	v_add_f32_dpp v26, v26, v26 quad_perm:[1,0,3,2] row_mask:0xf bank_mask:0xf bound_ctrl:1
	v_add_f32_dpp v27, v27, v27 quad_perm:[1,0,3,2] row_mask:0xf bank_mask:0xf bound_ctrl:1
	v_add_f32_dpp v28, v28, v28 quad_perm:[1,0,3,2] row_mask:0xf bank_mask:0xf bound_ctrl:1
	v_add_f32_dpp v29, v29, v29 quad_perm:[1,0,3,2] row_mask:0xf bank_mask:0xf bound_ctrl:1
	v_add_f32_dpp v30, v30, v30 quad_perm:[1,0,3,2] row_mask:0xf bank_mask:0xf bound_ctrl:1
	v_add_f32_dpp v31, v31, v31 quad_perm:[1,0,3,2] row_mask:0xf bank_mask:0xf bound_ctrl:1
	v_add_f32_dpp v24, v24, v24 quad_perm:[2,3,0,1] row_mask:0xf bank_mask:0xf bound_ctrl:1
	v_add_f32_dpp v25, v25, v25 quad_perm:[2,3,0,1] row_mask:0xf bank_mask:0xf bound_ctrl:1
	v_add_f32_dpp v26, v26, v26 quad_perm:[2,3,0,1] row_mask:0xf bank_mask:0xf bound_ctrl:1
	v_add_f32_dpp v27, v27, v27 quad_perm:[2,3,0,1] row_mask:0xf bank_mask:0xf bound_ctrl:1
	v_add_f32_dpp v28, v28, v28 quad_perm:[2,3,0,1] row_mask:0xf bank_mask:0xf bound_ctrl:1
	v_add_f32_dpp v29, v29, v29 quad_perm:[2,3,0,1] row_mask:0xf bank_mask:0xf bound_ctrl:1
	v_add_f32_dpp v30, v30, v30 quad_perm:[2,3,0,1] row_mask:0xf bank_mask:0xf bound_ctrl:1
	v_add_f32_dpp v31, v31, v31 quad_perm:[2,3,0,1] row_mask:0xf bank_mask:0xf bound_ctrl:1
	v_add_f32_dpp v24, v24, v24 row_half_mirror row_mask:0xf bank_mask:0xf bound_ctrl:1
	v_add_f32_dpp v25, v25, v25 row_half_mirror row_mask:0xf bank_mask:0xf bound_ctrl:1
	v_add_f32_dpp v26, v26, v26 row_half_mirror row_mask:0xf bank_mask:0xf bound_ctrl:1
	v_add_f32_dpp v27, v27, v27 row_half_mirror row_mask:0xf bank_mask:0xf bound_ctrl:1
	v_add_f32_dpp v28, v28, v28 row_half_mirror row_mask:0xf bank_mask:0xf bound_ctrl:1
	v_add_f32_dpp v29, v29, v29 row_half_mirror row_mask:0xf bank_mask:0xf bound_ctrl:1
	v_add_f32_dpp v30, v30, v30 row_half_mirror row_mask:0xf bank_mask:0xf bound_ctrl:1
	v_add_f32_dpp v31, v31, v31 row_half_mirror row_mask:0xf bank_mask:0xf bound_ctrl:1
	v_fma_f32 v24, v16, s91, -v24
	v_fma_f32 v25, v17, s91, -v25
	v_fma_f32 v26, v18, s91, -v26
	v_fma_f32 v27, v19, s91, -v27
	v_fma_f32 v28, v20, s91, -v28
	v_fma_f32 v29, v21, s91, -v29
	v_fma_f32 v30, v22, s91, -v30
	v_fma_f32 v31, v23, s91, -v31
	s_waitcnt lgkmcnt(0)
	ds_read_b32 v72, v0 offset:10880
	ds_read_b32 v73, v0 offset:10912
	ds_read_b32 v74, v0 offset:10944
	ds_read_b32 v75, v0 offset:10976
	ds_read_b32 v76, v0 offset:11008
	ds_read_b32 v79, v0 offset:11152
	ds_read_b32 v80, v0 offset:11184
	ds_read_b32 v81, v0 offset:11216
	ds_read_b32 v82, v0 offset:11248
	ds_read_b32 v83, v0 offset:11280
	ds_read_b32 v86, v0 offset:11424
	ds_read_b32 v87, v0 offset:11456
	ds_read_b32 v88, v0 offset:11488
	ds_read_b32 v89, v0 offset:11520
	ds_read_b32 v90, v0 offset:11552
	ds_read_b32 v93, v0 offset:11696
	ds_read_b32 v94, v0 offset:11728
	ds_read_b32 v95, v0 offset:11760
	ds_read_b32 v96, v0 offset:11792
	ds_read_b32 v97, v0 offset:11824
	ds_read_b32 v100, v0 offset:11968
	ds_read_b32 v101, v0 offset:12000
	ds_read_b32 v102, v0 offset:12032
	ds_read_b32 v103, v0 offset:12064
	ds_read_b32 v104, v0 offset:12096
	ds_read_b32 v107, v0 offset:12240
	ds_read_b32 v108, v0 offset:12272
	ds_read_b32 v109, v0 offset:12304
	ds_read_b32 v110, v0 offset:12336
	ds_read_b32 v111, v0 offset:12368
	ds_read_b32 v114, v0 offset:12512
	ds_read_b32 v115, v0 offset:12544
	ds_read_b32 v116, v0 offset:12576
	ds_read_b32 v117, v0 offset:12608
	ds_read_b32 v118, v0 offset:12640
	ds_read_b32 v121, v0 offset:12784
	ds_read_b32 v122, v0 offset:12816
	ds_read_b32 v123, v0 offset:12848
	ds_read_b32 v124, v0 offset:12880
	ds_read_b32 v125, v0 offset:12912
	v_mov_b32_e32 v12, v24
	v_cndmask_b32_e64 v12, v12, v25, s[6:7]
	v_cndmask_b32_e64 v12, v12, v26, s[68:69]
	v_cndmask_b32_e64 v12, v12, v27, s[92:93]
	v_cndmask_b32_e64 v12, v12, v28, s[94:95]
	v_cndmask_b32_e64 v12, v12, v29, s[96:97]
	v_cndmask_b32_e64 v12, v12, v30, s[98:99]
	v_cndmask_b32_e64 v12, v12, v31, s[100:101]
	s_nop 1
	v_mov_b32_dpp v41, v12 quad_perm:[0,0,0,0] row_mask:0xf bank_mask:0xf
	s_nop 1
	v_mov_b32_dpp v41, v41 row_half_mirror row_mask:0xf bank_mask:0xa
	v_fma_f32 v12, -v32, v41, v12
	s_nop 1
	v_mov_b32_dpp v41, v12 quad_perm:[1,1,1,1] row_mask:0xf bank_mask:0xf
	s_nop 1
	v_mov_b32_dpp v41, v41 row_half_mirror row_mask:0xf bank_mask:0xa
	v_fma_f32 v12, -v33, v41, v12
	s_nop 1
	v_mov_b32_dpp v41, v12 quad_perm:[2,2,2,2] row_mask:0xf bank_mask:0xf
	s_nop 1
	v_mov_b32_dpp v41, v41 row_half_mirror row_mask:0xf bank_mask:0xa
	v_fma_f32 v12, -v34, v41, v12
	s_nop 1
	v_mov_b32_dpp v41, v12 quad_perm:[3,3,3,3] row_mask:0xf bank_mask:0xf
	s_nop 1
	v_mov_b32_dpp v41, v41 row_half_mirror row_mask:0xf bank_mask:0xa
	v_fma_f32 v12, -v35, v41, v12
	s_nop 1
	v_mov_b32_dpp v41, v12 quad_perm:[0,0,0,0] row_mask:0xf bank_mask:0xf
	v_fma_f32 v12, -v36, v41, v12
	s_nop 1
	v_mov_b32_dpp v41, v12 quad_perm:[1,1,1,1] row_mask:0xf bank_mask:0xf
	v_fma_f32 v12, -v37, v41, v12
	s_nop 1
	v_mov_b32_dpp v41, v12 quad_perm:[2,2,2,2] row_mask:0xf bank_mask:0xf
	v_fma_f32 v12, -v38, v41, v12
	ds_read_b128 v[32:35], v40 offset:11040
	ds_read_b128 v[36:39], v40 offset:11056
	v_mul_f32_e32 v128, v4, v12
	v_mul_f32_e32 v129, v5, v12
	v_cvt_pk_bf16_f32 v128, v128, v128
	v_cvt_pk_bf16_f32 v129, v129, v129
	ds_write_b16 v2, v128 offset:4608
	ds_write_b16 v3, v129 offset:4608
	s_mov_b32 s91, 0
; #define LAS __attribute__((address_space(3)))
; __device__ __forceinline__ bf16_t f2bf(float f) { return (bf16_t)(cvt_pk_bf16(f, 0.f) & 0xffffu); }
; __device__ __forceinline__ void dn_prep(const Params& p, LAS unsigned char* lds) {
;     ...
;             for (int i = 1; i < 64; ++i) {
; #pragma unroll
;                 for (int j4 = 8; j4 < (i + 3) / 4; ++j4) rhi[j4 - 8] = *(const LAS f32x4*)(Asz + i * 68 + j4 * 4);
;                 if (i + 1 < 64) {
; #pragma unroll
;                     for (int j4 = 0; j4 < ((i + 4) / 4 < 8 ? (i + 4) / 4 : 8); ++j4) rlo[(i + 1) & 1][j4] = *(const LAS f32x4*)(Asz + (i + 1) * 68 + j4 * 4);
;                 }
;                 float a0 = (lane == i) ? 1.f : 0.f, a1 = 0.f, a2 = 0.f, a3 = 0.f;
; #pragma unroll
;                 for (int j4 = 0; j4 < (i + 3) / 4; ++j4) {
;                     const f32x4 av = (j4 < 8) ? rlo[i & 1][j4 & 7] : rhi[(j4 - 8) & 7];
;                     if (j4 * 4 + 0 < i) a0 -= av[0] * T[j4 * 4 + 0];
;                     if (j4 * 4 + 1 < i) a1 -= av[1] * T[j4 * 4 + 1];
;                     if (j4 * 4 + 2 < i) a2 -= av[2] * T[j4 * 4 + 2];
;                     if (j4 * 4 + 3 < i) a3 -= av[3] * T[j4 * 4 + 3];
;                 }
;                 T[i] = (a0 + a1) + (a2 + a3);
;                 tub[i * 72] = f2bf(T[i] * bc); twb[i * 72] = f2bf(T[i] * wcf);
.Lfs_b5:
	s_cmp_gt_u32 s1, 5
	s_cbranch_scc1 .Lfs_z5
	s_waitcnt lgkmcnt(4)
	v_mul_f32_e32 v24, v72, v8
	v_mul_f32_e32 v25, v79, v8
	v_mul_f32_e32 v26, v86, v8
	v_mul_f32_e32 v27, v93, v8
	v_mul_f32_e32 v28, v100, v8
	v_mul_f32_e32 v29, v107, v8
	v_mul_f32_e32 v30, v114, v8
	v_mul_f32_e32 v31, v121, v8
	v_fmac_f32_e32 v24, v73, v9
	v_fmac_f32_e32 v25, v80, v9
	v_fmac_f32_e32 v26, v87, v9
	v_fmac_f32_e32 v27, v94, v9
	v_fmac_f32_e32 v28, v101, v9
	v_fmac_f32_e32 v29, v108, v9
	v_fmac_f32_e32 v30, v115, v9
	v_fmac_f32_e32 v31, v122, v9
	v_fmac_f32_e32 v24, v74, v10
	v_fmac_f32_e32 v25, v81, v10
	v_fmac_f32_e32 v26, v88, v10
	v_fmac_f32_e32 v27, v95, v10
	v_fmac_f32_e32 v28, v102, v10
	v_fmac_f32_e32 v29, v109, v10
	v_fmac_f32_e32 v30, v116, v10
	v_fmac_f32_e32 v31, v123, v10
	v_fmac_f32_e32 v24, v75, v11
	v_fmac_f32_e32 v25, v82, v11
	v_fmac_f32_e32 v26, v89, v11
	v_fmac_f32_e32 v27, v96, v11
	v_fmac_f32_e32 v28, v103, v11
	v_fmac_f32_e32 v29, v110, v11
	v_fmac_f32_e32 v30, v117, v11
	v_fmac_f32_e32 v31, v124, v11
	v_fmac_f32_e32 v24, v76, v12
	v_fmac_f32_e32 v25, v83, v12
	v_fmac_f32_e32 v26, v90, v12
	v_fmac_f32_e32 v27, v97, v12
	v_fmac_f32_e32 v28, v104, v12
	v_fmac_f32_e32 v29, v111, v12
	v_fmac_f32_e32 v30, v118, v12
	v_fmac_f32_e32 v31, v125, v12
	v_add_f32_dpp v24, v24, v24 quad_perm:[1,0,3,2] row_mask:0xf bank_mask:0xf bound_ctrl:1
	v_add_f32_dpp v25, v25, v25 quad_perm:[1,0,3,2] row_mask:0xf bank_mask:0xf bound_ctrl:1
	v_add_f32_dpp v26, v26, v26 quad_perm:[1,0,3,2] row_mask:0xf bank_mask:0xf bound_ctrl:1
	v_add_f32_dpp v27, v27, v27 quad_perm:[1,0,3,2] row_mask:0xf bank_mask:0xf bound_ctrl:1
	v_add_f32_dpp v28, v28, v28 quad_perm:[1,0,3,2] row_mask:0xf bank_mask:0xf bound_ctrl:1
	v_add_f32_dpp v29, v29, v29 quad_perm:[1,0,3,2] row_mask:0xf bank_mask:0xf bound_ctrl:1
	v_add_f32_dpp v30, v30, v30 quad_perm:[1,0,3,2] row_mask:0xf bank_mask:0xf bound_ctrl:1
	v_add_f32_dpp v31, v31, v31 quad_perm:[1,0,3,2] row_mask:0xf bank_mask:0xf bound_ctrl:1
	v_add_f32_dpp v24, v24, v24 quad_perm:[2,3,0,1] row_mask:0xf bank_mask:0xf bound_ctrl:1
	v_add_f32_dpp v25, v25, v25 quad_perm:[2,3,0,1] row_mask:0xf bank_mask:0xf bound_ctrl:1
	v_add_f32_dpp v26, v26, v26 quad_perm:[2,3,0,1] row_mask:0xf bank_mask:0xf bound_ctrl:1
	v_add_f32_dpp v27, v27, v27 quad_perm:[2,3,0,1] row_mask:0xf bank_mask:0xf bound_ctrl:1
	v_add_f32_dpp v28, v28, v28 quad_perm:[2,3,0,1] row_mask:0xf bank_mask:0xf bound_ctrl:1
	v_add_f32_dpp v29, v29, v29 quad_perm:[2,3,0,1] row_mask:0xf bank_mask:0xf bound_ctrl:1
	v_add_f32_dpp v30, v30, v30 quad_perm:[2,3,0,1] row_mask:0xf bank_mask:0xf bound_ctrl:1
	v_add_f32_dpp v31, v31, v31 quad_perm:[2,3,0,1] row_mask:0xf bank_mask:0xf bound_ctrl:1
	v_add_f32_dpp v24, v24, v24 row_half_mirror row_mask:0xf bank_mask:0xf bound_ctrl:1
	v_add_f32_dpp v25, v25, v25 row_half_mirror row_mask:0xf bank_mask:0xf bound_ctrl:1
	v_add_f32_dpp v26, v26, v26 row_half_mirror row_mask:0xf bank_mask:0xf bound_ctrl:1
	v_add_f32_dpp v27, v27, v27 row_half_mirror row_mask:0xf bank_mask:0xf bound_ctrl:1
	v_add_f32_dpp v28, v28, v28 row_half_mirror row_mask:0xf bank_mask:0xf bound_ctrl:1
	v_add_f32_dpp v29, v29, v29 row_half_mirror row_mask:0xf bank_mask:0xf bound_ctrl:1
	v_add_f32_dpp v30, v30, v30 row_half_mirror row_mask:0xf bank_mask:0xf bound_ctrl:1
	v_add_f32_dpp v31, v31, v31 row_half_mirror row_mask:0xf bank_mask:0xf bound_ctrl:1
	v_fma_f32 v24, v16, s91, -v24
	v_fma_f32 v25, v17, s91, -v25
	v_fma_f32 v26, v18, s91, -v26
	v_fma_f32 v27, v19, s91, -v27
	v_fma_f32 v28, v20, s91, -v28
	v_fma_f32 v29, v21, s91, -v29
	v_fma_f32 v30, v22, s91, -v30
	v_fma_f32 v31, v23, s91, -v31
	s_waitcnt lgkmcnt(0)
	ds_read_b32 v72, v0 offset:13056
	ds_read_b32 v73, v0 offset:13088
	ds_read_b32 v74, v0 offset:13120
	ds_read_b32 v75, v0 offset:13152
	ds_read_b32 v76, v0 offset:13184
	ds_read_b32 v77, v0 offset:13216
	ds_read_b32 v79, v0 offset:13328
	ds_read_b32 v80, v0 offset:13360
	ds_read_b32 v81, v0 offset:13392
	ds_read_b32 v82, v0 offset:13424
	ds_read_b32 v83, v0 offset:13456
	ds_read_b32 v84, v0 offset:13488
	ds_read_b32 v86, v0 offset:13600
	ds_read_b32 v87, v0 offset:13632
	ds_read_b32 v88, v0 offset:13664
	ds_read_b32 v89, v0 offset:13696
	ds_read_b32 v90, v0 offset:13728
	ds_read_b32 v91, v0 offset:13760
	ds_read_b32 v93, v0 offset:13872
	ds_read_b32 v94, v0 offset:13904
	ds_read_b32 v95, v0 offset:13936
	ds_read_b32 v96, v0 offset:13968
	ds_read_b32 v97, v0 offset:14000
	ds_read_b32 v98, v0 offset:14032
	ds_read_b32 v100, v0 offset:14144
	ds_read_b32 v101, v0 offset:14176
	ds_read_b32 v102, v0 offset:14208
	ds_read_b32 v103, v0 offset:14240
	ds_read_b32 v104, v0 offset:14272
	ds_read_b32 v105, v0 offset:14304
	ds_read_b32 v107, v0 offset:14416
	ds_read_b32 v108, v0 offset:14448
	ds_read_b32 v109, v0 offset:14480
	ds_read_b32 v110, v0 offset:14512
	ds_read_b32 v111, v0 offset:14544
	ds_read_b32 v112, v0 offset:14576
	ds_read_b32 v114, v0 offset:14688
	ds_read_b32 v115, v0 offset:14720
	ds_read_b32 v116, v0 offset:14752
	ds_read_b32 v117, v0 offset:14784
	ds_read_b32 v118, v0 offset:14816
	ds_read_b32 v119, v0 offset:14848
	ds_read_b32 v121, v0 offset:14960
	ds_read_b32 v122, v0 offset:14992
	ds_read_b32 v123, v0 offset:15024
	ds_read_b32 v124, v0 offset:15056
	ds_read_b32 v125, v0 offset:15088
	ds_read_b32 v126, v0 offset:15120
	v_mov_b32_e32 v13, v24
	v_cndmask_b32_e64 v13, v13, v25, s[6:7]
	v_cndmask_b32_e64 v13, v13, v26, s[68:69]
	v_cndmask_b32_e64 v13, v13, v27, s[92:93]
	v_cndmask_b32_e64 v13, v13, v28, s[94:95]
	v_cndmask_b32_e64 v13, v13, v29, s[96:97]
	v_cndmask_b32_e64 v13, v13, v30, s[98:99]
	v_cndmask_b32_e64 v13, v13, v31, s[100:101]
	s_nop 1
	v_mov_b32_dpp v41, v13 quad_perm:[0,0,0,0] row_mask:0xf bank_mask:0xf
	s_nop 1
	v_mov_b32_dpp v41, v41 row_half_mirror row_mask:0xf bank_mask:0xa
	v_fma_f32 v13, -v32, v41, v13
	s_nop 1
	v_mov_b32_dpp v41, v13 quad_perm:[1,1,1,1] row_mask:0xf bank_mask:0xf
	s_nop 1
	v_mov_b32_dpp v41, v41 row_half_mirror row_mask:0xf bank_mask:0xa
	v_fma_f32 v13, -v33, v41, v13
	s_nop 1
	v_mov_b32_dpp v41, v13 quad_perm:[2,2,2,2] row_mask:0xf bank_mask:0xf
	s_nop 1
	v_mov_b32_dpp v41, v41 row_half_mirror row_mask:0xf bank_mask:0xa
	v_fma_f32 v13, -v34, v41, v13
	s_nop 1
	v_mov_b32_dpp v41, v13 quad_perm:[3,3,3,3] row_mask:0xf bank_mask:0xf
	s_nop 1
	v_mov_b32_dpp v41, v41 row_half_mirror row_mask:0xf bank_mask:0xa
	v_fma_f32 v13, -v35, v41, v13
	s_nop 1
	v_mov_b32_dpp v41, v13 quad_perm:[0,0,0,0] row_mask:0xf bank_mask:0xf
	v_fma_f32 v13, -v36, v41, v13
	s_nop 1
	v_mov_b32_dpp v41, v13 quad_perm:[1,1,1,1] row_mask:0xf bank_mask:0xf
	v_fma_f32 v13, -v37, v41, v13
	s_nop 1
	v_mov_b32_dpp v41, v13 quad_perm:[2,2,2,2] row_mask:0xf bank_mask:0xf
	v_fma_f32 v13, -v38, v41, v13
	ds_read_b128 v[32:35], v40 offset:13248
	ds_read_b128 v[36:39], v40 offset:13264
	v_mul_f32_e32 v128, v4, v13
	v_mul_f32_e32 v129, v5, v13
	v_cvt_pk_bf16_f32 v128, v128, v128
	v_cvt_pk_bf16_f32 v129, v129, v129
	ds_write_b16 v2, v128 offset:5760
	ds_write_b16 v3, v129 offset:5760
	s_mov_b32 s91, 0
; #define LAS __attribute__((address_space(3)))
; __device__ __forceinline__ bf16_t f2bf(float f) { return (bf16_t)(cvt_pk_bf16(f, 0.f) & 0xffffu); }
; __device__ __forceinline__ void dn_prep(const Params& p, LAS unsigned char* lds) {
;     ...
;             for (int i = 1; i < 64; ++i) {
; #pragma unroll
;                 for (int j4 = 8; j4 < (i + 3) / 4; ++j4) rhi[j4 - 8] = *(const LAS f32x4*)(Asz + i * 68 + j4 * 4);
;                 if (i + 1 < 64) {
; #pragma unroll
;                     for (int j4 = 0; j4 < ((i + 4) / 4 < 8 ? (i + 4) / 4 : 8); ++j4) rlo[(i + 1) & 1][j4] = *(const LAS f32x4*)(Asz + (i + 1) * 68 + j4 * 4);
;                 }
;                 float a0 = (lane == i) ? 1.f : 0.f, a1 = 0.f, a2 = 0.f, a3 = 0.f;
; #pragma unroll
;                 for (int j4 = 0; j4 < (i + 3) / 4; ++j4) {
;                     const f32x4 av = (j4 < 8) ? rlo[i & 1][j4 & 7] : rhi[(j4 - 8) & 7];
;                     if (j4 * 4 + 0 < i) a0 -= av[0] * T[j4 * 4 + 0];
;                     if (j4 * 4 + 1 < i) a1 -= av[1] * T[j4 * 4 + 1];
;                     if (j4 * 4 + 2 < i) a2 -= av[2] * T[j4 * 4 + 2];
;                     if (j4 * 4 + 3 < i) a3 -= av[3] * T[j4 * 4 + 3];
;                 }
;                 T[i] = (a0 + a1) + (a2 + a3);
;                 tub[i * 72] = f2bf(T[i] * bc); twb[i * 72] = f2bf(T[i] * wcf);
.Lfs_b6:
	s_cmp_gt_u32 s1, 6
	s_cbranch_scc1 .Lfs_z6
	s_waitcnt lgkmcnt(4)
	v_mul_f32_e32 v24, v72, v8
	v_mul_f32_e32 v25, v79, v8
	v_mul_f32_e32 v26, v86, v8
	v_mul_f32_e32 v27, v93, v8
	v_mul_f32_e32 v28, v100, v8
	v_mul_f32_e32 v29, v107, v8
	v_mul_f32_e32 v30, v114, v8
	v_mul_f32_e32 v31, v121, v8
	v_fmac_f32_e32 v24, v73, v9
	v_fmac_f32_e32 v25, v80, v9
	v_fmac_f32_e32 v26, v87, v9
	v_fmac_f32_e32 v27, v94, v9
	v_fmac_f32_e32 v28, v101, v9
	v_fmac_f32_e32 v29, v108, v9
	v_fmac_f32_e32 v30, v115, v9
	v_fmac_f32_e32 v31, v122, v9
	v_fmac_f32_e32 v24, v74, v10
	v_fmac_f32_e32 v25, v81, v10
	v_fmac_f32_e32 v26, v88, v10
	v_fmac_f32_e32 v27, v95, v10
	v_fmac_f32_e32 v28, v102, v10
	v_fmac_f32_e32 v29, v109, v10
	v_fmac_f32_e32 v30, v116, v10
	v_fmac_f32_e32 v31, v123, v10
	v_fmac_f32_e32 v24, v75, v11
	v_fmac_f32_e32 v25, v82, v11
	v_fmac_f32_e32 v26, v89, v11
	v_fmac_f32_e32 v27, v96, v11
	v_fmac_f32_e32 v28, v103, v11
	v_fmac_f32_e32 v29, v110, v11
	v_fmac_f32_e32 v30, v117, v11
	v_fmac_f32_e32 v31, v124, v11
	v_fmac_f32_e32 v24, v76, v12
	v_fmac_f32_e32 v25, v83, v12
	v_fmac_f32_e32 v26, v90, v12
	v_fmac_f32_e32 v27, v97, v12
	v_fmac_f32_e32 v28, v104, v12
	v_fmac_f32_e32 v29, v111, v12
	v_fmac_f32_e32 v30, v118, v12
	v_fmac_f32_e32 v31, v125, v12
	v_fmac_f32_e32 v24, v77, v13
	v_fmac_f32_e32 v25, v84, v13
	v_fmac_f32_e32 v26, v91, v13
	v_fmac_f32_e32 v27, v98, v13
	v_fmac_f32_e32 v28, v105, v13
	v_fmac_f32_e32 v29, v112, v13
	v_fmac_f32_e32 v30, v119, v13
	v_fmac_f32_e32 v31, v126, v13
	v_add_f32_dpp v24, v24, v24 quad_perm:[1,0,3,2] row_mask:0xf bank_mask:0xf bound_ctrl:1
	v_add_f32_dpp v25, v25, v25 quad_perm:[1,0,3,2] row_mask:0xf bank_mask:0xf bound_ctrl:1
	v_add_f32_dpp v26, v26, v26 quad_perm:[1,0,3,2] row_mask:0xf bank_mask:0xf bound_ctrl:1
	v_add_f32_dpp v27, v27, v27 quad_perm:[1,0,3,2] row_mask:0xf bank_mask:0xf bound_ctrl:1
	v_add_f32_dpp v28, v28, v28 quad_perm:[1,0,3,2] row_mask:0xf bank_mask:0xf bound_ctrl:1
	v_add_f32_dpp v29, v29, v29 quad_perm:[1,0,3,2] row_mask:0xf bank_mask:0xf bound_ctrl:1
	v_add_f32_dpp v30, v30, v30 quad_perm:[1,0,3,2] row_mask:0xf bank_mask:0xf bound_ctrl:1
	v_add_f32_dpp v31, v31, v31 quad_perm:[1,0,3,2] row_mask:0xf bank_mask:0xf bound_ctrl:1
	v_add_f32_dpp v24, v24, v24 quad_perm:[2,3,0,1] row_mask:0xf bank_mask:0xf bound_ctrl:1
	v_add_f32_dpp v25, v25, v25 quad_perm:[2,3,0,1] row_mask:0xf bank_mask:0xf bound_ctrl:1
	v_add_f32_dpp v26, v26, v26 quad_perm:[2,3,0,1] row_mask:0xf bank_mask:0xf bound_ctrl:1
	v_add_f32_dpp v27, v27, v27 quad_perm:[2,3,0,1] row_mask:0xf bank_mask:0xf bound_ctrl:1
	v_add_f32_dpp v28, v28, v28 quad_perm:[2,3,0,1] row_mask:0xf bank_mask:0xf bound_ctrl:1
	v_add_f32_dpp v29, v29, v29 quad_perm:[2,3,0,1] row_mask:0xf bank_mask:0xf bound_ctrl:1
	v_add_f32_dpp v30, v30, v30 quad_perm:[2,3,0,1] row_mask:0xf bank_mask:0xf bound_ctrl:1
	v_add_f32_dpp v31, v31, v31 quad_perm:[2,3,0,1] row_mask:0xf bank_mask:0xf bound_ctrl:1
	v_add_f32_dpp v24, v24, v24 row_half_mirror row_mask:0xf bank_mask:0xf bound_ctrl:1
	v_add_f32_dpp v25, v25, v25 row_half_mirror row_mask:0xf bank_mask:0xf bound_ctrl:1
	v_add_f32_dpp v26, v26, v26 row_half_mirror row_mask:0xf bank_mask:0xf bound_ctrl:1
	v_add_f32_dpp v27, v27, v27 row_half_mirror row_mask:0xf bank_mask:0xf bound_ctrl:1
	v_add_f32_dpp v28, v28, v28 row_half_mirror row_mask:0xf bank_mask:0xf bound_ctrl:1
	v_add_f32_dpp v29, v29, v29 row_half_mirror row_mask:0xf bank_mask:0xf bound_ctrl:1
	v_add_f32_dpp v30, v30, v30 row_half_mirror row_mask:0xf bank_mask:0xf bound_ctrl:1
	v_add_f32_dpp v31, v31, v31 row_half_mirror row_mask:0xf bank_mask:0xf bound_ctrl:1
	v_fma_f32 v24, v16, s91, -v24
	v_fma_f32 v25, v17, s91, -v25
	v_fma_f32 v26, v18, s91, -v26
	v_fma_f32 v27, v19, s91, -v27
	v_fma_f32 v28, v20, s91, -v28
	v_fma_f32 v29, v21, s91, -v29
	v_fma_f32 v30, v22, s91, -v30
	v_fma_f32 v31, v23, s91, -v31
	s_waitcnt lgkmcnt(0)
	ds_read_b32 v72, v0 offset:15232
	ds_read_b32 v73, v0 offset:15264
	ds_read_b32 v74, v0 offset:15296
	ds_read_b32 v75, v0 offset:15328
	ds_read_b32 v76, v0 offset:15360
	ds_read_b32 v77, v0 offset:15392
	ds_read_b32 v78, v0 offset:15424
	ds_read_b32 v79, v0 offset:15504
	ds_read_b32 v80, v0 offset:15536
	ds_read_b32 v81, v0 offset:15568
	ds_read_b32 v82, v0 offset:15600
	ds_read_b32 v83, v0 offset:15632
	ds_read_b32 v84, v0 offset:15664
	ds_read_b32 v85, v0 offset:15696
	ds_read_b32 v86, v0 offset:15776
	ds_read_b32 v87, v0 offset:15808
	ds_read_b32 v88, v0 offset:15840
	ds_read_b32 v89, v0 offset:15872
	ds_read_b32 v90, v0 offset:15904
	ds_read_b32 v91, v0 offset:15936
	ds_read_b32 v92, v0 offset:15968
	ds_read_b32 v93, v0 offset:16048
	ds_read_b32 v94, v0 offset:16080
	ds_read_b32 v95, v0 offset:16112
	ds_read_b32 v96, v0 offset:16144
	ds_read_b32 v97, v0 offset:16176
	ds_read_b32 v98, v0 offset:16208
	ds_read_b32 v99, v0 offset:16240
	ds_read_b32 v100, v0 offset:16320
	ds_read_b32 v101, v0 offset:16352
	ds_read_b32 v102, v0 offset:16384
	ds_read_b32 v103, v0 offset:16416
	ds_read_b32 v104, v0 offset:16448
	ds_read_b32 v105, v0 offset:16480
	ds_read_b32 v106, v0 offset:16512
	ds_read_b32 v107, v0 offset:16592
	ds_read_b32 v108, v0 offset:16624
	ds_read_b32 v109, v0 offset:16656
	ds_read_b32 v110, v0 offset:16688
	ds_read_b32 v111, v0 offset:16720
	ds_read_b32 v112, v0 offset:16752
	ds_read_b32 v113, v0 offset:16784
	ds_read_b32 v114, v0 offset:16864
	ds_read_b32 v115, v0 offset:16896
	ds_read_b32 v116, v0 offset:16928
	ds_read_b32 v117, v0 offset:16960
	ds_read_b32 v118, v0 offset:16992
	ds_read_b32 v119, v0 offset:17024
	ds_read_b32 v120, v0 offset:17056
	ds_read_b32 v121, v0 offset:17136
	ds_read_b32 v122, v0 offset:17168
; #define LAS __attribute__((address_space(3)))
; __device__ __forceinline__ bf16_t f2bf(float f) { return (bf16_t)(cvt_pk_bf16(f, 0.f) & 0xffffu); }
; __device__ __forceinline__ void dn_prep(const Params& p, LAS unsigned char* lds) {
;     ...
;             for (int i = 1; i < 64; ++i) {
; #pragma unroll
;                 for (int j4 = 8; j4 < (i + 3) / 4; ++j4) rhi[j4 - 8] = *(const LAS f32x4*)(Asz + i * 68 + j4 * 4);
;                 if (i + 1 < 64) {
; #pragma unroll
;                     for (int j4 = 0; j4 < ((i + 4) / 4 < 8 ? (i + 4) / 4 : 8); ++j4) rlo[(i + 1) & 1][j4] = *(const LAS f32x4*)(Asz + (i + 1) * 68 + j4 * 4);
;                 }
;                 float a0 = (lane == i) ? 1.f : 0.f, a1 = 0.f, a2 = 0.f, a3 = 0.f;
; #pragma unroll
;                 for (int j4 = 0; j4 < (i + 3) / 4; ++j4) {
;                     const f32x4 av = (j4 < 8) ? rlo[i & 1][j4 & 7] : rhi[(j4 - 8) & 7];
;                     if (j4 * 4 + 0 < i) a0 -= av[0] * T[j4 * 4 + 0];
;                     if (j4 * 4 + 1 < i) a1 -= av[1] * T[j4 * 4 + 1];
;                     if (j4 * 4 + 2 < i) a2 -= av[2] * T[j4 * 4 + 2];
;                     if (j4 * 4 + 3 < i) a3 -= av[3] * T[j4 * 4 + 3];
;                 }
;                 T[i] = (a0 + a1) + (a2 + a3);
;                 tub[i * 72] = f2bf(T[i] * bc); twb[i * 72] = f2bf(T[i] * wcf);
	ds_read_b32 v123, v0 offset:17200
	ds_read_b32 v124, v0 offset:17232
	ds_read_b32 v125, v0 offset:17264
	ds_read_b32 v126, v0 offset:17296
	ds_read_b32 v127, v0 offset:17328
	v_mov_b32_e32 v14, v24
	v_cndmask_b32_e64 v14, v14, v25, s[6:7]
	v_cndmask_b32_e64 v14, v14, v26, s[68:69]
	v_cndmask_b32_e64 v14, v14, v27, s[92:93]
	v_cndmask_b32_e64 v14, v14, v28, s[94:95]
	v_cndmask_b32_e64 v14, v14, v29, s[96:97]
	v_cndmask_b32_e64 v14, v14, v30, s[98:99]
	v_cndmask_b32_e64 v14, v14, v31, s[100:101]
	s_nop 1
	v_mov_b32_dpp v41, v14 quad_perm:[0,0,0,0] row_mask:0xf bank_mask:0xf
	s_nop 1
	v_mov_b32_dpp v41, v41 row_half_mirror row_mask:0xf bank_mask:0xa
	v_fma_f32 v14, -v32, v41, v14
	s_nop 1
	v_mov_b32_dpp v41, v14 quad_perm:[1,1,1,1] row_mask:0xf bank_mask:0xf
	s_nop 1
	v_mov_b32_dpp v41, v41 row_half_mirror row_mask:0xf bank_mask:0xa
	v_fma_f32 v14, -v33, v41, v14
	s_nop 1
	v_mov_b32_dpp v41, v14 quad_perm:[2,2,2,2] row_mask:0xf bank_mask:0xf
	s_nop 1
	v_mov_b32_dpp v41, v41 row_half_mirror row_mask:0xf bank_mask:0xa
	v_fma_f32 v14, -v34, v41, v14
	s_nop 1
	v_mov_b32_dpp v41, v14 quad_perm:[3,3,3,3] row_mask:0xf bank_mask:0xf
	s_nop 1
	v_mov_b32_dpp v41, v41 row_half_mirror row_mask:0xf bank_mask:0xa
	v_fma_f32 v14, -v35, v41, v14
	s_nop 1
	v_mov_b32_dpp v41, v14 quad_perm:[0,0,0,0] row_mask:0xf bank_mask:0xf
	v_fma_f32 v14, -v36, v41, v14
	s_nop 1
	v_mov_b32_dpp v41, v14 quad_perm:[1,1,1,1] row_mask:0xf bank_mask:0xf
	v_fma_f32 v14, -v37, v41, v14
	s_nop 1
	v_mov_b32_dpp v41, v14 quad_perm:[2,2,2,2] row_mask:0xf bank_mask:0xf
	v_fma_f32 v14, -v38, v41, v14
	ds_read_b128 v[32:35], v40 offset:15456
	ds_read_b128 v[36:39], v40 offset:15472
	v_mul_f32_e32 v128, v4, v14
	v_mul_f32_e32 v129, v5, v14
	v_cvt_pk_bf16_f32 v128, v128, v128
	v_cvt_pk_bf16_f32 v129, v129, v129
	ds_write_b16 v2, v128 offset:6912
	ds_write_b16 v3, v129 offset:6912
	s_mov_b32 s91, 0
; #define LAS __attribute__((address_space(3)))
; __device__ __forceinline__ void dn_prep(const Params& p, LAS unsigned char* lds) {
;     ...
;         if (wid == 0 && samp) {
;             float T[16];
;             int zoff; asm volatile("v_mov_b32 %0, 0" : "=v"(zoff));
;             const LAS float* Asz = As + zoff;
;             const float bc = beta_s[lane], wcf = bc * __expf(G_s[lane]);
;             int lo2 = lane; asm volatile("" : "+v"(lo2));
;             LAS bf16_t* tub = Tu + lo2; LAS bf16_t* twb = Tw + lo2;
; #pragma unroll
;             for (int i = 0; i < 16; ++i) {
;                 float a0 = (lane == i) ? 1.f : 0.f, a1 = 0.f;
; #pragma unroll
;                 for (int j4 = 0; j4 < (i + 3) / 4; ++j4) {
;                     const f32x4 av = *(const LAS f32x4*)(Asz + i * 68 + j4 * 4);
; #pragma unroll
;                     for (int e = 0; e < 4; ++e) { const int jx = j4 * 4 + e; if (jx < i) { if (jx & 1) a1 -= av[e] * T[jx]; else a0 -= av[e] * T[jx]; } }
;                 }
;                 T[i] = a0 + a1;
;                 tub[i * 72] = f2bf(T[i] * bc); twb[i * 72] = f2bf(T[i] * wcf);
;             }
; #pragma unroll
;             for (int i = 16; i < 64; ++i) { tub[i * 72] = 0; twb[i * 72] = 0; }
;         } else
;     ...
;             for (int i = 1; i < 64; ++i) {
; #pragma unroll
;                 for (int j4 = 8; j4 < (i + 3) / 4; ++j4) rhi[j4 - 8] = *(const LAS f32x4*)(Asz + i * 68 + j4 * 4);
;                 if (i + 1 < 64) {
; #pragma unroll
;                     for (int j4 = 0; j4 < ((i + 4) / 4 < 8 ? (i + 4) / 4 : 8); ++j4) rlo[(i + 1) & 1][j4] = *(const LAS f32x4*)(Asz + (i + 1) * 68 + j4 * 4);
;                 }
;                 float a0 = (lane == i) ? 1.f : 0.f, a1 = 0.f, a2 = 0.f, a3 = 0.f;
; #pragma unroll
;                 for (int j4 = 0; j4 < (i + 3) / 4; ++j4) {
;                     const f32x4 av = (j4 < 8) ? rlo[i & 1][j4 & 7] : rhi[(j4 - 8) & 7];
;                     if (j4 * 4 + 0 < i) a0 -= av[0] * T[j4 * 4 + 0];
;                     if (j4 * 4 + 1 < i) a1 -= av[1] * T[j4 * 4 + 1];
;                     if (j4 * 4 + 2 < i) a2 -= av[2] * T[j4 * 4 + 2];
;                     if (j4 * 4 + 3 < i) a3 -= av[3] * T[j4 * 4 + 3];
;                 }
;                 T[i] = (a0 + a1) + (a2 + a3);
;                 tub[i * 72] = f2bf(T[i] * bc); twb[i * 72] = f2bf(T[i] * wcf);
.Lfs_b7:
	s_waitcnt lgkmcnt(4)
	v_mul_f32_e32 v24, v72, v8
	v_mul_f32_e32 v25, v79, v8
	v_mul_f32_e32 v26, v86, v8
	v_mul_f32_e32 v27, v93, v8
	v_mul_f32_e32 v28, v100, v8
	v_mul_f32_e32 v29, v107, v8
	v_mul_f32_e32 v30, v114, v8
	v_mul_f32_e32 v31, v121, v8
	v_fmac_f32_e32 v24, v73, v9
	v_fmac_f32_e32 v25, v80, v9
	v_fmac_f32_e32 v26, v87, v9
	v_fmac_f32_e32 v27, v94, v9
	v_fmac_f32_e32 v28, v101, v9
	v_fmac_f32_e32 v29, v108, v9
	v_fmac_f32_e32 v30, v115, v9
	v_fmac_f32_e32 v31, v122, v9
	v_fmac_f32_e32 v24, v74, v10
	v_fmac_f32_e32 v25, v81, v10
	v_fmac_f32_e32 v26, v88, v10
	v_fmac_f32_e32 v27, v95, v10
	v_fmac_f32_e32 v28, v102, v10
	v_fmac_f32_e32 v29, v109, v10
	v_fmac_f32_e32 v30, v116, v10
	v_fmac_f32_e32 v31, v123, v10
	v_fmac_f32_e32 v24, v75, v11
	v_fmac_f32_e32 v25, v82, v11
	v_fmac_f32_e32 v26, v89, v11
	v_fmac_f32_e32 v27, v96, v11
	v_fmac_f32_e32 v28, v103, v11
	v_fmac_f32_e32 v29, v110, v11
	v_fmac_f32_e32 v30, v117, v11
	v_fmac_f32_e32 v31, v124, v11
	v_fmac_f32_e32 v24, v76, v12
	v_fmac_f32_e32 v25, v83, v12
	v_fmac_f32_e32 v26, v90, v12
	v_fmac_f32_e32 v27, v97, v12
	v_fmac_f32_e32 v28, v104, v12
	v_fmac_f32_e32 v29, v111, v12
	v_fmac_f32_e32 v30, v118, v12
	v_fmac_f32_e32 v31, v125, v12
	v_fmac_f32_e32 v24, v77, v13
	v_fmac_f32_e32 v25, v84, v13
	v_fmac_f32_e32 v26, v91, v13
	v_fmac_f32_e32 v27, v98, v13
	v_fmac_f32_e32 v28, v105, v13
	v_fmac_f32_e32 v29, v112, v13
	v_fmac_f32_e32 v30, v119, v13
	v_fmac_f32_e32 v31, v126, v13
	v_fmac_f32_e32 v24, v78, v14
	v_fmac_f32_e32 v25, v85, v14
	v_fmac_f32_e32 v26, v92, v14
	v_fmac_f32_e32 v27, v99, v14
	v_fmac_f32_e32 v28, v106, v14
	v_fmac_f32_e32 v29, v113, v14
	v_fmac_f32_e32 v30, v120, v14
	v_fmac_f32_e32 v31, v127, v14
	v_add_f32_dpp v24, v24, v24 quad_perm:[1,0,3,2] row_mask:0xf bank_mask:0xf bound_ctrl:1
	v_add_f32_dpp v25, v25, v25 quad_perm:[1,0,3,2] row_mask:0xf bank_mask:0xf bound_ctrl:1
	v_add_f32_dpp v26, v26, v26 quad_perm:[1,0,3,2] row_mask:0xf bank_mask:0xf bound_ctrl:1
	v_add_f32_dpp v27, v27, v27 quad_perm:[1,0,3,2] row_mask:0xf bank_mask:0xf bound_ctrl:1
	v_add_f32_dpp v28, v28, v28 quad_perm:[1,0,3,2] row_mask:0xf bank_mask:0xf bound_ctrl:1
	v_add_f32_dpp v29, v29, v29 quad_perm:[1,0,3,2] row_mask:0xf bank_mask:0xf bound_ctrl:1
	v_add_f32_dpp v30, v30, v30 quad_perm:[1,0,3,2] row_mask:0xf bank_mask:0xf bound_ctrl:1
	v_add_f32_dpp v31, v31, v31 quad_perm:[1,0,3,2] row_mask:0xf bank_mask:0xf bound_ctrl:1
	v_add_f32_dpp v24, v24, v24 quad_perm:[2,3,0,1] row_mask:0xf bank_mask:0xf bound_ctrl:1
	v_add_f32_dpp v25, v25, v25 quad_perm:[2,3,0,1] row_mask:0xf bank_mask:0xf bound_ctrl:1
	v_add_f32_dpp v26, v26, v26 quad_perm:[2,3,0,1] row_mask:0xf bank_mask:0xf bound_ctrl:1
	v_add_f32_dpp v27, v27, v27 quad_perm:[2,3,0,1] row_mask:0xf bank_mask:0xf bound_ctrl:1
	v_add_f32_dpp v28, v28, v28 quad_perm:[2,3,0,1] row_mask:0xf bank_mask:0xf bound_ctrl:1
	v_add_f32_dpp v29, v29, v29 quad_perm:[2,3,0,1] row_mask:0xf bank_mask:0xf bound_ctrl:1
	v_add_f32_dpp v30, v30, v30 quad_perm:[2,3,0,1] row_mask:0xf bank_mask:0xf bound_ctrl:1
	v_add_f32_dpp v31, v31, v31 quad_perm:[2,3,0,1] row_mask:0xf bank_mask:0xf bound_ctrl:1
	v_add_f32_dpp v24, v24, v24 row_half_mirror row_mask:0xf bank_mask:0xf bound_ctrl:1
	v_add_f32_dpp v25, v25, v25 row_half_mirror row_mask:0xf bank_mask:0xf bound_ctrl:1
	v_add_f32_dpp v26, v26, v26 row_half_mirror row_mask:0xf bank_mask:0xf bound_ctrl:1
	v_add_f32_dpp v27, v27, v27 row_half_mirror row_mask:0xf bank_mask:0xf bound_ctrl:1
	v_add_f32_dpp v28, v28, v28 row_half_mirror row_mask:0xf bank_mask:0xf bound_ctrl:1
	v_add_f32_dpp v29, v29, v29 row_half_mirror row_mask:0xf bank_mask:0xf bound_ctrl:1
	v_add_f32_dpp v30, v30, v30 row_half_mirror row_mask:0xf bank_mask:0xf bound_ctrl:1
	v_add_f32_dpp v31, v31, v31 row_half_mirror row_mask:0xf bank_mask:0xf bound_ctrl:1
	v_fma_f32 v24, v16, s91, -v24
	v_fma_f32 v25, v17, s91, -v25
	v_fma_f32 v26, v18, s91, -v26
	v_fma_f32 v27, v19, s91, -v27
	v_fma_f32 v28, v20, s91, -v28
	v_fma_f32 v29, v21, s91, -v29
	v_fma_f32 v30, v22, s91, -v30
	v_fma_f32 v31, v23, s91, -v31
	s_waitcnt lgkmcnt(0)
	v_mov_b32_e32 v15, v24
	v_cndmask_b32_e64 v15, v15, v25, s[6:7]
	v_cndmask_b32_e64 v15, v15, v26, s[68:69]
	v_cndmask_b32_e64 v15, v15, v27, s[92:93]
	v_cndmask_b32_e64 v15, v15, v28, s[94:95]
	v_cndmask_b32_e64 v15, v15, v29, s[96:97]
	v_cndmask_b32_e64 v15, v15, v30, s[98:99]
	v_cndmask_b32_e64 v15, v15, v31, s[100:101]
	s_nop 1
	v_mov_b32_dpp v41, v15 quad_perm:[0,0,0,0] row_mask:0xf bank_mask:0xf
	s_nop 1
	v_mov_b32_dpp v41, v41 row_half_mirror row_mask:0xf bank_mask:0xa
	v_fma_f32 v15, -v32, v41, v15
	s_nop 1
	v_mov_b32_dpp v41, v15 quad_perm:[1,1,1,1] row_mask:0xf bank_mask:0xf
	s_nop 1
	v_mov_b32_dpp v41, v41 row_half_mirror row_mask:0xf bank_mask:0xa
	v_fma_f32 v15, -v33, v41, v15
	s_nop 1
	v_mov_b32_dpp v41, v15 quad_perm:[2,2,2,2] row_mask:0xf bank_mask:0xf
	s_nop 1
	v_mov_b32_dpp v41, v41 row_half_mirror row_mask:0xf bank_mask:0xa
	v_fma_f32 v15, -v34, v41, v15
	s_nop 1
	v_mov_b32_dpp v41, v15 quad_perm:[3,3,3,3] row_mask:0xf bank_mask:0xf
	s_nop 1
	v_mov_b32_dpp v41, v41 row_half_mirror row_mask:0xf bank_mask:0xa
	v_fma_f32 v15, -v35, v41, v15
	s_nop 1
	v_mov_b32_dpp v41, v15 quad_perm:[0,0,0,0] row_mask:0xf bank_mask:0xf
	v_fma_f32 v15, -v36, v41, v15
	s_nop 1
	v_mov_b32_dpp v41, v15 quad_perm:[1,1,1,1] row_mask:0xf bank_mask:0xf
	v_fma_f32 v15, -v37, v41, v15
	s_nop 1
	v_mov_b32_dpp v41, v15 quad_perm:[2,2,2,2] row_mask:0xf bank_mask:0xf
	v_fma_f32 v15, -v38, v41, v15
	v_mul_f32_e32 v128, v4, v15
	v_mul_f32_e32 v129, v5, v15
	v_cvt_pk_bf16_f32 v128, v128, v128
	v_cvt_pk_bf16_f32 v129, v129, v129
	ds_write_b16 v2, v128 offset:8064
	ds_write_b16 v3, v129 offset:8064
	s_mov_b32 s91, 0
	s_branch .LBB0_378
.Lfs_z0:
	s_cmp_eq_u32 s1, 1
	s_cbranch_scc0 .Lfs_zw0
	ds_read_b32 v72, v0 offset:2176
	ds_read_b32 v79, v0 offset:2448
	ds_read_b32 v86, v0 offset:2720
	ds_read_b32 v93, v0 offset:2992
	ds_read_b32 v100, v0 offset:3264
	ds_read_b32 v107, v0 offset:3536
	ds_read_b32 v114, v0 offset:3808
	ds_read_b32 v121, v0 offset:4080
	ds_read_b128 v[32:35], v40 offset:2208
	ds_read_b128 v[36:39], v40 offset:2224

; #define LAS __attribute__((address_space(3)))
; __device__ __forceinline__ bf16_t f2bf(float f) { return (bf16_t)(cvt_pk_bf16(f, 0.f) & 0xffffu); }
; __device__ __forceinline__ void dn_prep(const Params& p, LAS unsigned char* lds) {
;     ...
;             for (int i = 1; i < 64; ++i) {
; #pragma unroll
;                 for (int j4 = 8; j4 < (i + 3) / 4; ++j4) rhi[j4 - 8] = *(const LAS f32x4*)(Asz + i * 68 + j4 * 4);
;                 if (i + 1 < 64) {
; #pragma unroll
;                     for (int j4 = 0; j4 < ((i + 4) / 4 < 8 ? (i + 4) / 4 : 8); ++j4) rlo[(i + 1) & 1][j4] = *(const LAS f32x4*)(Asz + (i + 1) * 68 + j4 * 4);
;                 }
;                 float a0 = (lane == i) ? 1.f : 0.f, a1 = 0.f, a2 = 0.f, a3 = 0.f;
; #pragma unroll
;                 for (int j4 = 0; j4 < (i + 3) / 4; ++j4) {
;                     const f32x4 av = (j4 < 8) ? rlo[i & 1][j4 & 7] : rhi[(j4 - 8) & 7];
;                     if (j4 * 4 + 0 < i) a0 -= av[0] * T[j4 * 4 + 0];
;                     if (j4 * 4 + 1 < i) a1 -= av[1] * T[j4 * 4 + 1];
;                     if (j4 * 4 + 2 < i) a2 -= av[2] * T[j4 * 4 + 2];
;                     if (j4 * 4 + 3 < i) a3 -= av[3] * T[j4 * 4 + 3];
;                 }
;                 T[i] = (a0 + a1) + (a2 + a3);
;                 tub[i * 72] = f2bf(T[i] * bc); twb[i * 72] = f2bf(T[i] * wcf);
.Lfs_z1:
	s_cmp_eq_u32 s1, 2
	s_cbranch_scc0 .Lfs_zw1
	ds_read_b32 v72, v0 offset:4352
	ds_read_b32 v73, v0 offset:4384
	ds_read_b32 v79, v0 offset:4624
	ds_read_b32 v80, v0 offset:4656
	ds_read_b32 v86, v0 offset:4896
	ds_read_b32 v87, v0 offset:4928
	ds_read_b32 v93, v0 offset:5168
	ds_read_b32 v94, v0 offset:5200
	ds_read_b32 v100, v0 offset:5440
	ds_read_b32 v101, v0 offset:5472
	ds_read_b32 v107, v0 offset:5712
	ds_read_b32 v108, v0 offset:5744
	ds_read_b32 v114, v0 offset:5984
	ds_read_b32 v115, v0 offset:6016
	ds_read_b32 v121, v0 offset:6256
	ds_read_b32 v122, v0 offset:6288
	ds_read_b128 v[32:35], v40 offset:4416
	ds_read_b128 v[36:39], v40 offset:4432

; #define LAS __attribute__((address_space(3)))
; __device__ __forceinline__ bf16_t f2bf(float f) { return (bf16_t)(cvt_pk_bf16(f, 0.f) & 0xffffu); }
; __device__ __forceinline__ void dn_prep(const Params& p, LAS unsigned char* lds) {
;     ...
;             for (int i = 1; i < 64; ++i) {
; #pragma unroll
;                 for (int j4 = 8; j4 < (i + 3) / 4; ++j4) rhi[j4 - 8] = *(const LAS f32x4*)(Asz + i * 68 + j4 * 4);
;                 if (i + 1 < 64) {
; #pragma unroll
;                     for (int j4 = 0; j4 < ((i + 4) / 4 < 8 ? (i + 4) / 4 : 8); ++j4) rlo[(i + 1) & 1][j4] = *(const LAS f32x4*)(Asz + (i + 1) * 68 + j4 * 4);
;                 }
;                 float a0 = (lane == i) ? 1.f : 0.f, a1 = 0.f, a2 = 0.f, a3 = 0.f;
; #pragma unroll
;                 for (int j4 = 0; j4 < (i + 3) / 4; ++j4) {
;                     const f32x4 av = (j4 < 8) ? rlo[i & 1][j4 & 7] : rhi[(j4 - 8) & 7];
;                     if (j4 * 4 + 0 < i) a0 -= av[0] * T[j4 * 4 + 0];
;                     if (j4 * 4 + 1 < i) a1 -= av[1] * T[j4 * 4 + 1];
;                     if (j4 * 4 + 2 < i) a2 -= av[2] * T[j4 * 4 + 2];
;                     if (j4 * 4 + 3 < i) a3 -= av[3] * T[j4 * 4 + 3];
;                 }
;                 T[i] = (a0 + a1) + (a2 + a3);
;                 tub[i * 72] = f2bf(T[i] * bc); twb[i * 72] = f2bf(T[i] * wcf);
.Lfs_z2:
	s_cmp_eq_u32 s1, 3
	s_cbranch_scc0 .Lfs_zw2
	ds_read_b32 v72, v0 offset:6528
	ds_read_b32 v73, v0 offset:6560
	ds_read_b32 v74, v0 offset:6592
	ds_read_b32 v79, v0 offset:6800
	ds_read_b32 v80, v0 offset:6832
	ds_read_b32 v81, v0 offset:6864
	ds_read_b32 v86, v0 offset:7072
	ds_read_b32 v87, v0 offset:7104
	ds_read_b32 v88, v0 offset:7136
	ds_read_b32 v93, v0 offset:7344
	ds_read_b32 v94, v0 offset:7376
	ds_read_b32 v95, v0 offset:7408
	ds_read_b32 v100, v0 offset:7616
	ds_read_b32 v101, v0 offset:7648
	ds_read_b32 v102, v0 offset:7680
	ds_read_b32 v107, v0 offset:7888
	ds_read_b32 v108, v0 offset:7920
	ds_read_b32 v109, v0 offset:7952
	ds_read_b32 v114, v0 offset:8160
	ds_read_b32 v115, v0 offset:8192
	ds_read_b32 v116, v0 offset:8224
	ds_read_b32 v121, v0 offset:8432
	ds_read_b32 v122, v0 offset:8464
	ds_read_b32 v123, v0 offset:8496
	ds_read_b128 v[32:35], v40 offset:6624
	ds_read_b128 v[36:39], v40 offset:6640

; #define LAS __attribute__((address_space(3)))
; __device__ __forceinline__ bf16_t f2bf(float f) { return (bf16_t)(cvt_pk_bf16(f, 0.f) & 0xffffu); }
; __device__ __forceinline__ void dn_prep(const Params& p, LAS unsigned char* lds) {
;     ...
;             for (int i = 1; i < 64; ++i) {
; #pragma unroll
;                 for (int j4 = 8; j4 < (i + 3) / 4; ++j4) rhi[j4 - 8] = *(const LAS f32x4*)(Asz + i * 68 + j4 * 4);
;                 if (i + 1 < 64) {
; #pragma unroll
;                     for (int j4 = 0; j4 < ((i + 4) / 4 < 8 ? (i + 4) / 4 : 8); ++j4) rlo[(i + 1) & 1][j4] = *(const LAS f32x4*)(Asz + (i + 1) * 68 + j4 * 4);
;                 }
;                 float a0 = (lane == i) ? 1.f : 0.f, a1 = 0.f, a2 = 0.f, a3 = 0.f;
; #pragma unroll
;                 for (int j4 = 0; j4 < (i + 3) / 4; ++j4) {
;                     const f32x4 av = (j4 < 8) ? rlo[i & 1][j4 & 7] : rhi[(j4 - 8) & 7];
;                     if (j4 * 4 + 0 < i) a0 -= av[0] * T[j4 * 4 + 0];
;                     if (j4 * 4 + 1 < i) a1 -= av[1] * T[j4 * 4 + 1];
;                     if (j4 * 4 + 2 < i) a2 -= av[2] * T[j4 * 4 + 2];
;                     if (j4 * 4 + 3 < i) a3 -= av[3] * T[j4 * 4 + 3];
;                 }
;                 T[i] = (a0 + a1) + (a2 + a3);
;                 tub[i * 72] = f2bf(T[i] * bc); twb[i * 72] = f2bf(T[i] * wcf);
.Lfs_z3:
	s_cmp_eq_u32 s1, 4
	s_cbranch_scc0 .Lfs_zw3
	ds_read_b32 v72, v0 offset:8704
	ds_read_b32 v73, v0 offset:8736
	ds_read_b32 v74, v0 offset:8768
	ds_read_b32 v75, v0 offset:8800
	ds_read_b32 v79, v0 offset:8976
	ds_read_b32 v80, v0 offset:9008
	ds_read_b32 v81, v0 offset:9040
	ds_read_b32 v82, v0 offset:9072
	ds_read_b32 v86, v0 offset:9248
	ds_read_b32 v87, v0 offset:9280
	ds_read_b32 v88, v0 offset:9312
	ds_read_b32 v89, v0 offset:9344
	ds_read_b32 v93, v0 offset:9520
	ds_read_b32 v94, v0 offset:9552
	ds_read_b32 v95, v0 offset:9584
	ds_read_b32 v96, v0 offset:9616
	ds_read_b32 v100, v0 offset:9792
	ds_read_b32 v101, v0 offset:9824
	ds_read_b32 v102, v0 offset:9856
	ds_read_b32 v103, v0 offset:9888
	ds_read_b32 v107, v0 offset:10064
	ds_read_b32 v108, v0 offset:10096
	ds_read_b32 v109, v0 offset:10128
	ds_read_b32 v110, v0 offset:10160
	ds_read_b32 v114, v0 offset:10336
	ds_read_b32 v115, v0 offset:10368
	ds_read_b32 v116, v0 offset:10400
	ds_read_b32 v117, v0 offset:10432
	ds_read_b32 v121, v0 offset:10608
	ds_read_b32 v122, v0 offset:10640
	ds_read_b32 v123, v0 offset:10672
	ds_read_b32 v124, v0 offset:10704
	ds_read_b128 v[32:35], v40 offset:8832
	ds_read_b128 v[36:39], v40 offset:8848

; #define LAS __attribute__((address_space(3)))
; __device__ __forceinline__ bf16_t f2bf(float f) { return (bf16_t)(cvt_pk_bf16(f, 0.f) & 0xffffu); }
; __device__ __forceinline__ void dn_prep(const Params& p, LAS unsigned char* lds) {
;     ...
;             for (int i = 1; i < 64; ++i) {
; #pragma unroll
;                 for (int j4 = 8; j4 < (i + 3) / 4; ++j4) rhi[j4 - 8] = *(const LAS f32x4*)(Asz + i * 68 + j4 * 4);
;                 if (i + 1 < 64) {
; #pragma unroll
;                     for (int j4 = 0; j4 < ((i + 4) / 4 < 8 ? (i + 4) / 4 : 8); ++j4) rlo[(i + 1) & 1][j4] = *(const LAS f32x4*)(Asz + (i + 1) * 68 + j4 * 4);
;                 }
;                 float a0 = (lane == i) ? 1.f : 0.f, a1 = 0.f, a2 = 0.f, a3 = 0.f;
; #pragma unroll
;                 for (int j4 = 0; j4 < (i + 3) / 4; ++j4) {
;                     const f32x4 av = (j4 < 8) ? rlo[i & 1][j4 & 7] : rhi[(j4 - 8) & 7];
;                     if (j4 * 4 + 0 < i) a0 -= av[0] * T[j4 * 4 + 0];
;                     if (j4 * 4 + 1 < i) a1 -= av[1] * T[j4 * 4 + 1];
;                     if (j4 * 4 + 2 < i) a2 -= av[2] * T[j4 * 4 + 2];
;                     if (j4 * 4 + 3 < i) a3 -= av[3] * T[j4 * 4 + 3];
;                 }
;                 T[i] = (a0 + a1) + (a2 + a3);
;                 tub[i * 72] = f2bf(T[i] * bc); twb[i * 72] = f2bf(T[i] * wcf);
.Lfs_z4:
	s_cmp_eq_u32 s1, 5
	s_cbranch_scc0 .Lfs_zw4
	ds_read_b32 v72, v0 offset:10880
	ds_read_b32 v73, v0 offset:10912
	ds_read_b32 v74, v0 offset:10944
	ds_read_b32 v75, v0 offset:10976
	ds_read_b32 v76, v0 offset:11008
	ds_read_b32 v79, v0 offset:11152
	ds_read_b32 v80, v0 offset:11184
	ds_read_b32 v81, v0 offset:11216
	ds_read_b32 v82, v0 offset:11248
	ds_read_b32 v83, v0 offset:11280
	ds_read_b32 v86, v0 offset:11424
	ds_read_b32 v87, v0 offset:11456
	ds_read_b32 v88, v0 offset:11488
	ds_read_b32 v89, v0 offset:11520
	ds_read_b32 v90, v0 offset:11552
	ds_read_b32 v93, v0 offset:11696
	ds_read_b32 v94, v0 offset:11728
	ds_read_b32 v95, v0 offset:11760
	ds_read_b32 v96, v0 offset:11792
	ds_read_b32 v97, v0 offset:11824
	ds_read_b32 v100, v0 offset:11968
	ds_read_b32 v101, v0 offset:12000
	ds_read_b32 v102, v0 offset:12032
	ds_read_b32 v103, v0 offset:12064
	ds_read_b32 v104, v0 offset:12096
	ds_read_b32 v107, v0 offset:12240
	ds_read_b32 v108, v0 offset:12272
	ds_read_b32 v109, v0 offset:12304
	ds_read_b32 v110, v0 offset:12336
	ds_read_b32 v111, v0 offset:12368
	ds_read_b32 v114, v0 offset:12512
	ds_read_b32 v115, v0 offset:12544
	ds_read_b32 v116, v0 offset:12576
	ds_read_b32 v117, v0 offset:12608
	ds_read_b32 v118, v0 offset:12640
	ds_read_b32 v121, v0 offset:12784
	ds_read_b32 v122, v0 offset:12816
	ds_read_b32 v123, v0 offset:12848
	ds_read_b32 v124, v0 offset:12880
	ds_read_b32 v125, v0 offset:12912
	ds_read_b128 v[32:35], v40 offset:11040
	ds_read_b128 v[36:39], v40 offset:11056

; #define LAS __attribute__((address_space(3)))
; __device__ __forceinline__ bf16_t f2bf(float f) { return (bf16_t)(cvt_pk_bf16(f, 0.f) & 0xffffu); }
; __device__ __forceinline__ void dn_prep(const Params& p, LAS unsigned char* lds) {
;     ...
;             for (int i = 1; i < 64; ++i) {
; #pragma unroll
;                 for (int j4 = 8; j4 < (i + 3) / 4; ++j4) rhi[j4 - 8] = *(const LAS f32x4*)(Asz + i * 68 + j4 * 4);
;                 if (i + 1 < 64) {
; #pragma unroll
;                     for (int j4 = 0; j4 < ((i + 4) / 4 < 8 ? (i + 4) / 4 : 8); ++j4) rlo[(i + 1) & 1][j4] = *(const LAS f32x4*)(Asz + (i + 1) * 68 + j4 * 4);
;                 }
;                 float a0 = (lane == i) ? 1.f : 0.f, a1 = 0.f, a2 = 0.f, a3 = 0.f;
; #pragma unroll
;                 for (int j4 = 0; j4 < (i + 3) / 4; ++j4) {
;                     const f32x4 av = (j4 < 8) ? rlo[i & 1][j4 & 7] : rhi[(j4 - 8) & 7];
;                     if (j4 * 4 + 0 < i) a0 -= av[0] * T[j4 * 4 + 0];
;                     if (j4 * 4 + 1 < i) a1 -= av[1] * T[j4 * 4 + 1];
;                     if (j4 * 4 + 2 < i) a2 -= av[2] * T[j4 * 4 + 2];
;                     if (j4 * 4 + 3 < i) a3 -= av[3] * T[j4 * 4 + 3];
;                 }
;                 T[i] = (a0 + a1) + (a2 + a3);
;                 tub[i * 72] = f2bf(T[i] * bc); twb[i * 72] = f2bf(T[i] * wcf);
.Lfs_z5:
	s_cmp_eq_u32 s1, 6
	s_cbranch_scc0 .Lfs_zw5
	ds_read_b32 v72, v0 offset:13056
	ds_read_b32 v73, v0 offset:13088
	ds_read_b32 v74, v0 offset:13120
	ds_read_b32 v75, v0 offset:13152
	ds_read_b32 v76, v0 offset:13184
	ds_read_b32 v77, v0 offset:13216
	ds_read_b32 v79, v0 offset:13328
	ds_read_b32 v80, v0 offset:13360
	ds_read_b32 v81, v0 offset:13392
	ds_read_b32 v82, v0 offset:13424
	ds_read_b32 v83, v0 offset:13456
	ds_read_b32 v84, v0 offset:13488
	ds_read_b32 v86, v0 offset:13600
	ds_read_b32 v87, v0 offset:13632
	ds_read_b32 v88, v0 offset:13664
	ds_read_b32 v89, v0 offset:13696
	ds_read_b32 v90, v0 offset:13728
	ds_read_b32 v91, v0 offset:13760
	ds_read_b32 v93, v0 offset:13872
	ds_read_b32 v94, v0 offset:13904
	ds_read_b32 v95, v0 offset:13936
	ds_read_b32 v96, v0 offset:13968
	ds_read_b32 v97, v0 offset:14000
	ds_read_b32 v98, v0 offset:14032
	ds_read_b32 v100, v0 offset:14144
	ds_read_b32 v101, v0 offset:14176
	ds_read_b32 v102, v0 offset:14208
	ds_read_b32 v103, v0 offset:14240
	ds_read_b32 v104, v0 offset:14272
	ds_read_b32 v105, v0 offset:14304
	ds_read_b32 v107, v0 offset:14416
	ds_read_b32 v108, v0 offset:14448
	ds_read_b32 v109, v0 offset:14480
	ds_read_b32 v110, v0 offset:14512
	ds_read_b32 v111, v0 offset:14544
	ds_read_b32 v112, v0 offset:14576
	ds_read_b32 v114, v0 offset:14688
	ds_read_b32 v115, v0 offset:14720
	ds_read_b32 v116, v0 offset:14752
	ds_read_b32 v117, v0 offset:14784
	ds_read_b32 v118, v0 offset:14816
	ds_read_b32 v119, v0 offset:14848
	ds_read_b32 v121, v0 offset:14960
	ds_read_b32 v122, v0 offset:14992
	ds_read_b32 v123, v0 offset:15024
	ds_read_b32 v124, v0 offset:15056
	ds_read_b32 v125, v0 offset:15088
	ds_read_b32 v126, v0 offset:15120
	ds_read_b128 v[32:35], v40 offset:13248
	ds_read_b128 v[36:39], v40 offset:13264

; #define LAS __attribute__((address_space(3)))
; __device__ __forceinline__ bf16_t f2bf(float f) { return (bf16_t)(cvt_pk_bf16(f, 0.f) & 0xffffu); }
; __device__ __forceinline__ void dn_prep(const Params& p, LAS unsigned char* lds) {
;     ...
;             for (int i = 1; i < 64; ++i) {
; #pragma unroll
;                 for (int j4 = 8; j4 < (i + 3) / 4; ++j4) rhi[j4 - 8] = *(const LAS f32x4*)(Asz + i * 68 + j4 * 4);
;                 if (i + 1 < 64) {
; #pragma unroll
;                     for (int j4 = 0; j4 < ((i + 4) / 4 < 8 ? (i + 4) / 4 : 8); ++j4) rlo[(i + 1) & 1][j4] = *(const LAS f32x4*)(Asz + (i + 1) * 68 + j4 * 4);
;                 }
;                 float a0 = (lane == i) ? 1.f : 0.f, a1 = 0.f, a2 = 0.f, a3 = 0.f;
; #pragma unroll
;                 for (int j4 = 0; j4 < (i + 3) / 4; ++j4) {
;                     const f32x4 av = (j4 < 8) ? rlo[i & 1][j4 & 7] : rhi[(j4 - 8) & 7];
;                     if (j4 * 4 + 0 < i) a0 -= av[0] * T[j4 * 4 + 0];
;                     if (j4 * 4 + 1 < i) a1 -= av[1] * T[j4 * 4 + 1];
;                     if (j4 * 4 + 2 < i) a2 -= av[2] * T[j4 * 4 + 2];
;                     if (j4 * 4 + 3 < i) a3 -= av[3] * T[j4 * 4 + 3];
;                 }
;                 T[i] = (a0 + a1) + (a2 + a3);
;                 tub[i * 72] = f2bf(T[i] * bc); twb[i * 72] = f2bf(T[i] * wcf);
.Lfs_z6:
	s_cmp_eq_u32 s1, 7
	s_cbranch_scc0 .Lfs_zw6
	ds_read_b32 v72, v0 offset:15232
	ds_read_b32 v73, v0 offset:15264
	ds_read_b32 v74, v0 offset:15296
	ds_read_b32 v75, v0 offset:15328
	ds_read_b32 v76, v0 offset:15360
	ds_read_b32 v77, v0 offset:15392
	ds_read_b32 v78, v0 offset:15424
	ds_read_b32 v79, v0 offset:15504
	ds_read_b32 v80, v0 offset:15536
	ds_read_b32 v81, v0 offset:15568
	ds_read_b32 v82, v0 offset:15600
	ds_read_b32 v83, v0 offset:15632
	ds_read_b32 v84, v0 offset:15664
	ds_read_b32 v85, v0 offset:15696
	ds_read_b32 v86, v0 offset:15776
	ds_read_b32 v87, v0 offset:15808
	ds_read_b32 v88, v0 offset:15840
	ds_read_b32 v89, v0 offset:15872
	ds_read_b32 v90, v0 offset:15904
	ds_read_b32 v91, v0 offset:15936
	ds_read_b32 v92, v0 offset:15968
	ds_read_b32 v93, v0 offset:16048
	ds_read_b32 v94, v0 offset:16080
	ds_read_b32 v95, v0 offset:16112
	ds_read_b32 v96, v0 offset:16144
	ds_read_b32 v97, v0 offset:16176
	ds_read_b32 v98, v0 offset:16208
	ds_read_b32 v99, v0 offset:16240
	ds_read_b32 v100, v0 offset:16320
	ds_read_b32 v101, v0 offset:16352
	ds_read_b32 v102, v0 offset:16384
	ds_read_b32 v103, v0 offset:16416
	ds_read_b32 v104, v0 offset:16448
	ds_read_b32 v105, v0 offset:16480
	ds_read_b32 v106, v0 offset:16512
	ds_read_b32 v107, v0 offset:16592
	ds_read_b32 v108, v0 offset:16624
	ds_read_b32 v109, v0 offset:16656
	ds_read_b32 v110, v0 offset:16688
	ds_read_b32 v111, v0 offset:16720
	ds_read_b32 v112, v0 offset:16752
	ds_read_b32 v113, v0 offset:16784
	ds_read_b32 v114, v0 offset:16864
	ds_read_b32 v115, v0 offset:16896
	ds_read_b32 v116, v0 offset:16928
	ds_read_b32 v117, v0 offset:16960
	ds_read_b32 v118, v0 offset:16992
	ds_read_b32 v119, v0 offset:17024
	ds_read_b32 v120, v0 offset:17056
	ds_read_b32 v121, v0 offset:17136
	ds_read_b32 v122, v0 offset:17168
	ds_read_b32 v123, v0 offset:17200
	ds_read_b32 v124, v0 offset:17232
	ds_read_b32 v125, v0 offset:17264
	ds_read_b32 v126, v0 offset:17296
	ds_read_b32 v127, v0 offset:17328
	ds_read_b128 v[32:35], v40 offset:15456
	ds_read_b128 v[36:39], v40 offset:15472
